# v1: prep_xb 8 loads in flight per lane; MoE gather index loads batched before one wait
# speedup vs baseline: 1.0009x; 1.0009x over previous
.LBB0_204:
	s_mov_b32 s3, 0
	s_lshl_b64 s[0:1], s[2:3], 9
	v_ashrrev_i32_e32 v35, 31, v34
	s_ashr_i32 s75, s74, 31
	v_lshl_add_u64 v[2:3], s[0:1], 0, v[34:35]
	s_mov_b64 s[0:1], 0x1000000
	v_writelane_b32 v254, s51, 4
	s_lshl_b64 s[6:7], s[74:75], 9
	v_cmp_gt_u64_e32 vcc, s[0:1], v[2:3]
	s_and_saveexec_b64 s[8:9], vcc
	s_cbranch_execz .LBB0_207
	s_lshl_b64 s[0:1], s[2:3], 13
	s_add_u32 s0, s16, s0
	s_addc_u32 s1, s17, s1
	v_lshl_add_u64 v[4:5], v[34:35], 4, s[0:1]
	s_lshl_b64 s[10:11], s[74:75], 13
	s_lshl_b64 s[0:1], s[2:3], 12
	s_add_u32 s0, s36, s0
	s_addc_u32 s1, s37, s1
	v_lshl_add_u64 v[6:7], v[34:35], 3, s[0:1]
	s_mov_b64 s[0:1], 0xa100000
	v_lshl_add_u64 v[6:7], v[6:7], 0, s[0:1]
	s_lshl_b64 s[16:17], s[74:75], 12
	s_mov_b64 s[20:21], 0
	s_mov_b64 s[22:23], 0xffffff
	v_mov_b64_e32 v[8:9], v[2:3]
	s_mul_i32 s98, s6, 7
	v_readfirstlane_b32 s99, v8
	s_add_u32 s98, s98, 63
	s_lshl_b64 s[100:101], s[6:7], 3
.Lxb_main:
	s_add_u32 s0, s99, s98
	s_cmp_gt_u32 s0, 0xffffff
	s_cbranch_scc1 .Lxb_tail
	global_load_dwordx4 v[100:103], v[4:5], off
	v_lshl_add_u64 v[4:5], v[4:5], 0, s[10:11]
	global_load_dwordx4 v[104:107], v[4:5], off
	v_lshl_add_u64 v[4:5], v[4:5], 0, s[10:11]
	global_load_dwordx4 v[108:111], v[4:5], off
	v_lshl_add_u64 v[4:5], v[4:5], 0, s[10:11]
	global_load_dwordx4 v[112:115], v[4:5], off
	v_lshl_add_u64 v[4:5], v[4:5], 0, s[10:11]
	global_load_dwordx4 v[116:119], v[4:5], off
	v_lshl_add_u64 v[4:5], v[4:5], 0, s[10:11]
	global_load_dwordx4 v[120:123], v[4:5], off
	v_lshl_add_u64 v[4:5], v[4:5], 0, s[10:11]
	global_load_dwordx4 v[124:127], v[4:5], off
	v_lshl_add_u64 v[4:5], v[4:5], 0, s[10:11]
	global_load_dwordx4 v[128:131], v[4:5], off
	v_lshl_add_u64 v[4:5], v[4:5], 0, s[10:11]
	s_add_u32 s99, s99, s100
	v_lshl_add_u64 v[8:9], v[8:9], 0, s[100:101]
	s_waitcnt vmcnt(7)
	v_cvt_pk_bf16_f32 v100, v100, v101
	v_cvt_pk_bf16_f32 v101, v102, v103
	global_store_dwordx2 v[6:7], v[100:101], off
	v_lshl_add_u64 v[6:7], v[6:7], 0, s[16:17]
	s_waitcnt vmcnt(7)
	v_cvt_pk_bf16_f32 v104, v104, v105
	v_cvt_pk_bf16_f32 v105, v106, v107
	global_store_dwordx2 v[6:7], v[104:105], off
	v_lshl_add_u64 v[6:7], v[6:7], 0, s[16:17]
	s_waitcnt vmcnt(7)
	v_cvt_pk_bf16_f32 v108, v108, v109
	v_cvt_pk_bf16_f32 v109, v110, v111
	global_store_dwordx2 v[6:7], v[108:109], off
	v_lshl_add_u64 v[6:7], v[6:7], 0, s[16:17]
	s_waitcnt vmcnt(7)
	v_cvt_pk_bf16_f32 v112, v112, v113
	v_cvt_pk_bf16_f32 v113, v114, v115
	global_store_dwordx2 v[6:7], v[112:113], off
	v_lshl_add_u64 v[6:7], v[6:7], 0, s[16:17]
	s_waitcnt vmcnt(7)
	v_cvt_pk_bf16_f32 v116, v116, v117
	v_cvt_pk_bf16_f32 v117, v118, v119
	global_store_dwordx2 v[6:7], v[116:117], off
	v_lshl_add_u64 v[6:7], v[6:7], 0, s[16:17]
	s_waitcnt vmcnt(7)
	v_cvt_pk_bf16_f32 v120, v120, v121
	v_cvt_pk_bf16_f32 v121, v122, v123
	global_store_dwordx2 v[6:7], v[120:121], off
	v_lshl_add_u64 v[6:7], v[6:7], 0, s[16:17]
	s_waitcnt vmcnt(7)
	v_cvt_pk_bf16_f32 v124, v124, v125
	v_cvt_pk_bf16_f32 v125, v126, v127
	global_store_dwordx2 v[6:7], v[124:125], off
	v_lshl_add_u64 v[6:7], v[6:7], 0, s[16:17]
	s_waitcnt vmcnt(7)
	v_cvt_pk_bf16_f32 v128, v128, v129
	v_cvt_pk_bf16_f32 v129, v130, v131
	global_store_dwordx2 v[6:7], v[128:129], off
	v_lshl_add_u64 v[6:7], v[6:7], 0, s[16:17]
	s_branch .Lxb_main
.Lxb_tail:
	v_cmp_ge_u64_e32 vcc, s[22:23], v[8:9]
	s_and_b64 exec, exec, vcc
	s_cbranch_execz .LBB0_207

.LBB0_625:
	s_sub_i32 s0, 0x200, s38
	s_min_i32 s41, s0, s90
	s_lshl_b32 s22, s41, 3
	s_ashr_i32 s23, s22, 31
	v_mov_b32_e32 v2, v0
	s_cmp_lt_i32 s2, s22
	s_cselect_b64 s[12:13], -1, 0
	s_cmp_ge_i32 s2, s22
	v_readfirstlane_b32 s42, v2
	s_cbranch_scc1 .Lgidx_skip_0
	s_movk_i32 s0, 0xff
	v_cmp_lt_i32_e64 s[8:9], s0, v2
	s_movk_i32 s0, 0x100
	v_lshl_add_u32 v3, v2, 2, s95
	v_cmp_gt_i32_e64 s[10:11], s0, v2
	s_and_saveexec_b64 s[24:25], s[10:11]
	s_cbranch_execz .LBB0_628
	s_or_b32 s0, s41, s80
	s_mul_i32 s0, s0, s76
	s_add_i32 s0, s0, s91
	s_ashr_i32 s1, s0, 31
	s_lshr_b32 s1, s1, 26
	s_add_i32 s1, s0, s1
	s_ashr_i32 s26, s1, 6
	s_lshl_b32 s26, s26, 3
	s_sub_i32 s27, s41, s26
	s_min_i32 s27, s27, 8
	s_abs_i32 s27, s27
	v_cvt_f32_u32_e32 v4, s27
	s_sub_i32 s28, 0, s27
	s_andn2_b32 s1, s1, 63
	s_sub_i32 s0, s0, s1
	v_rcp_iflag_f32_e32 v4, v4
	s_ashr_i32 s1, s0, 31
	s_abs_i32 s0, s0
	v_mul_f32_e32 v4, 0x4f7ffffe, v4
	v_cvt_u32_f32_e32 v4, v4
	s_nop 0
	v_readfirstlane_b32 s29, v4
	s_mul_i32 s28, s28, s29
	s_mul_hi_u32 s28, s29, s28
	s_add_i32 s29, s29, s28
	s_mul_hi_u32 s28, s0, s29
	s_mul_i32 s28, s28, s27
	s_sub_i32 s0, s0, s28
	s_sub_i32 s28, s0, s27
	s_cmp_ge_u32 s0, s27
	s_cselect_b32 s0, s28, s0
	s_sub_i32 s28, s0, s27
	s_cmp_ge_u32 s0, s27
	s_cselect_b32 s0, s28, s0
	s_xor_b32 s0, s0, s1
	s_sub_i32 s0, s0, s1
	s_add_i32 s1, s26, s38
	s_add_i32 s1, s1, s0
	v_lshl_add_u32 v4, s1, 8, v2
	v_ashrrev_i32_e32 v5, 31, v4
	v_lshl_add_u64 v[4:5], v[4:5], 2, s[16:17]
	global_load_dword v34, v[4:5], off
.LBB0_628:
	s_or_b64 exec, exec, s[24:25]
	v_readlane_b32 s0, v254, 23
	v_mov_b64_e32 v[4:5], s[22:23]
	v_readlane_b32 s1, v254, 24
	s_nop 1
	v_cmp_ge_i64_e32 vcc, s[0:1], v[4:5]
	s_cbranch_vccnz .LBB0_673
	s_and_saveexec_b64 s[24:25], s[10:11]
	s_cbranch_execz .LBB0_631
	v_readlane_b32 s0, v254, 22
	s_or_b32 s0, s41, s0
	v_readlane_b32 s1, v254, 21
	s_mul_i32 s0, s0, s1
	s_add_i32 s0, s0, s89
	s_ashr_i32 s1, s0, 31
	s_lshr_b32 s1, s1, 26
	s_add_i32 s1, s0, s1
	s_ashr_i32 s26, s1, 6
	s_lshl_b32 s26, s26, 3
	s_sub_i32 s27, s41, s26
	s_min_i32 s27, s27, 8
	s_abs_i32 s27, s27
	v_cvt_f32_u32_e32 v4, s27
	s_sub_i32 s28, 0, s27
	s_andn2_b32 s1, s1, 63
	s_sub_i32 s0, s0, s1
	v_rcp_iflag_f32_e32 v4, v4
	s_ashr_i32 s1, s0, 31
	s_abs_i32 s0, s0
	v_mul_f32_e32 v4, 0x4f7ffffe, v4
	v_cvt_u32_f32_e32 v4, v4
	s_nop 0
	v_readfirstlane_b32 s29, v4
	s_mul_i32 s28, s28, s29
	s_mul_hi_u32 s28, s29, s28
	s_add_i32 s29, s29, s28
	s_mul_hi_u32 s28, s0, s29
	s_mul_i32 s28, s28, s27
	s_sub_i32 s0, s0, s28
	s_sub_i32 s28, s0, s27
	s_cmp_ge_u32 s0, s27
	s_cselect_b32 s0, s28, s0
	s_sub_i32 s28, s0, s27
	s_cmp_ge_u32 s0, s27
	s_cselect_b32 s0, s28, s0
	s_xor_b32 s0, s0, s1
	s_sub_i32 s0, s0, s1
	s_add_i32 s1, s26, s38
	s_add_i32 s1, s1, s0
	v_lshl_add_u32 v4, s1, 8, v2
	v_ashrrev_i32_e32 v5, 31, v4
	v_lshl_add_u64 v[4:5], v[4:5], 2, s[16:17]
	global_load_dword v35, v[4:5], off
.LBB0_631:
	s_or_b64 exec, exec, s[24:25]
	v_readlane_b32 s0, v254, 28
	v_mov_b64_e32 v[4:5], s[22:23]
	v_readlane_b32 s1, v254, 29
	s_nop 1
	v_cmp_ge_i64_e32 vcc, s[0:1], v[4:5]
	s_cbranch_vccnz .LBB0_673
	s_and_saveexec_b64 s[24:25], s[10:11]
	s_cbranch_execz .LBB0_634
	v_readlane_b32 s0, v254, 27
	s_or_b32 s0, s41, s0
	v_readlane_b32 s1, v254, 26
	s_mul_i32 s0, s0, s1
	v_readlane_b32 s1, v254, 25
	s_add_i32 s0, s0, s1
	s_ashr_i32 s1, s0, 31
	s_lshr_b32 s1, s1, 26
	s_add_i32 s1, s0, s1
	s_ashr_i32 s26, s1, 6
	s_lshl_b32 s26, s26, 3
	s_sub_i32 s27, s41, s26
	s_min_i32 s27, s27, 8
	s_abs_i32 s27, s27
	v_cvt_f32_u32_e32 v4, s27
	s_sub_i32 s28, 0, s27
	s_andn2_b32 s1, s1, 63
	s_sub_i32 s0, s0, s1
	v_rcp_iflag_f32_e32 v4, v4
	s_ashr_i32 s1, s0, 31
	s_abs_i32 s0, s0
	v_mul_f32_e32 v4, 0x4f7ffffe, v4
	v_cvt_u32_f32_e32 v4, v4
	s_nop 0
	v_readfirstlane_b32 s29, v4
	s_mul_i32 s28, s28, s29
	s_mul_hi_u32 s28, s29, s28
	s_add_i32 s29, s29, s28
	s_mul_hi_u32 s28, s0, s29
	s_mul_i32 s28, s28, s27
	s_sub_i32 s0, s0, s28
	s_sub_i32 s28, s0, s27
	s_cmp_ge_u32 s0, s27
	s_cselect_b32 s0, s28, s0
	s_sub_i32 s28, s0, s27
	s_cmp_ge_u32 s0, s27
	s_cselect_b32 s0, s28, s0
	s_xor_b32 s0, s0, s1
	s_sub_i32 s0, s0, s1
	s_add_i32 s1, s26, s38
	s_add_i32 s1, s1, s0
	v_lshl_add_u32 v4, s1, 8, v2
	v_ashrrev_i32_e32 v5, 31, v4
	v_lshl_add_u64 v[4:5], v[4:5], 2, s[16:17]
	global_load_dword v36, v[4:5], off
.LBB0_634:
	s_or_b64 exec, exec, s[24:25]
	v_readlane_b32 s0, v254, 33
	v_mov_b64_e32 v[4:5], s[22:23]
	v_readlane_b32 s1, v254, 34
	s_nop 1
	v_cmp_ge_i64_e32 vcc, s[0:1], v[4:5]
	s_cbranch_vccnz .LBB0_673
	s_and_saveexec_b64 s[24:25], s[10:11]
	s_cbranch_execz .LBB0_637
	v_readlane_b32 s0, v254, 32
	s_or_b32 s0, s41, s0
	v_readlane_b32 s1, v254, 31
	s_mul_i32 s0, s0, s1
	v_readlane_b32 s1, v254, 30
	s_add_i32 s0, s0, s1
	s_ashr_i32 s1, s0, 31
	s_lshr_b32 s1, s1, 26
	s_add_i32 s1, s0, s1
	s_ashr_i32 s26, s1, 6
	s_lshl_b32 s26, s26, 3
	s_sub_i32 s27, s41, s26
	s_min_i32 s27, s27, 8
	s_abs_i32 s27, s27
	v_cvt_f32_u32_e32 v4, s27
	s_sub_i32 s28, 0, s27
	s_andn2_b32 s1, s1, 63
	s_sub_i32 s0, s0, s1
	v_rcp_iflag_f32_e32 v4, v4
	s_ashr_i32 s1, s0, 31
	s_abs_i32 s0, s0
	v_mul_f32_e32 v4, 0x4f7ffffe, v4
	v_cvt_u32_f32_e32 v4, v4
	s_nop 0
	v_readfirstlane_b32 s29, v4
	s_mul_i32 s28, s28, s29
	s_mul_hi_u32 s28, s29, s28
	s_add_i32 s29, s29, s28
	s_mul_hi_u32 s28, s0, s29
	s_mul_i32 s28, s28, s27
	s_sub_i32 s0, s0, s28
	s_sub_i32 s28, s0, s27
	s_cmp_ge_u32 s0, s27
	s_cselect_b32 s0, s28, s0
	s_sub_i32 s28, s0, s27
	s_cmp_ge_u32 s0, s27
	s_cselect_b32 s0, s28, s0
	s_xor_b32 s0, s0, s1
	s_sub_i32 s0, s0, s1
	s_add_i32 s1, s26, s38
	s_add_i32 s1, s1, s0
	v_lshl_add_u32 v4, s1, 8, v2
	v_ashrrev_i32_e32 v5, 31, v4
	v_lshl_add_u64 v[4:5], v[4:5], 2, s[16:17]
	global_load_dword v37, v[4:5], off
.LBB0_637:
	s_or_b64 exec, exec, s[24:25]
	v_readlane_b32 s0, v254, 38
	v_mov_b64_e32 v[4:5], s[22:23]
	v_readlane_b32 s1, v254, 39
	s_nop 1
	v_cmp_ge_i64_e32 vcc, s[0:1], v[4:5]
	s_cbranch_vccnz .LBB0_673
	s_and_saveexec_b64 s[24:25], s[10:11]
	s_cbranch_execz .LBB0_640
	v_readlane_b32 s0, v254, 37
	s_or_b32 s0, s41, s0
	v_readlane_b32 s1, v254, 36
	s_mul_i32 s0, s0, s1
	v_readlane_b32 s1, v254, 35
	s_add_i32 s0, s0, s1
	s_ashr_i32 s1, s0, 31
	s_lshr_b32 s1, s1, 26
	s_add_i32 s1, s0, s1
	s_ashr_i32 s26, s1, 6
	s_lshl_b32 s26, s26, 3
	s_sub_i32 s27, s41, s26
	s_min_i32 s27, s27, 8
	s_abs_i32 s27, s27
	v_cvt_f32_u32_e32 v4, s27
	s_sub_i32 s28, 0, s27
	s_andn2_b32 s1, s1, 63
	s_sub_i32 s0, s0, s1
	v_rcp_iflag_f32_e32 v4, v4
	s_ashr_i32 s1, s0, 31
	s_abs_i32 s0, s0
	v_mul_f32_e32 v4, 0x4f7ffffe, v4
	v_cvt_u32_f32_e32 v4, v4
	s_nop 0
	v_readfirstlane_b32 s29, v4
	s_mul_i32 s28, s28, s29
	s_mul_hi_u32 s28, s29, s28
	s_add_i32 s29, s29, s28
	s_mul_hi_u32 s28, s0, s29
	s_mul_i32 s28, s28, s27
	s_sub_i32 s0, s0, s28
	s_sub_i32 s28, s0, s27
	s_cmp_ge_u32 s0, s27
	s_cselect_b32 s0, s28, s0
	s_sub_i32 s28, s0, s27
	s_cmp_ge_u32 s0, s27
	s_cselect_b32 s0, s28, s0
	s_xor_b32 s0, s0, s1
	s_sub_i32 s0, s0, s1
	s_add_i32 s1, s26, s38
	s_add_i32 s1, s1, s0
	v_lshl_add_u32 v4, s1, 8, v2
	v_ashrrev_i32_e32 v5, 31, v4
	v_lshl_add_u64 v[4:5], v[4:5], 2, s[16:17]
	global_load_dword v38, v[4:5], off
.LBB0_640:
	s_or_b64 exec, exec, s[24:25]
	v_readlane_b32 s0, v254, 43
	v_mov_b64_e32 v[4:5], s[22:23]
	v_readlane_b32 s1, v254, 44
	s_nop 1
	v_cmp_ge_i64_e32 vcc, s[0:1], v[4:5]
	s_cbranch_vccnz .LBB0_673
	s_and_saveexec_b64 s[24:25], s[10:11]
	s_cbranch_execz .LBB0_643
	v_readlane_b32 s0, v254, 42
	s_or_b32 s0, s41, s0
	v_readlane_b32 s1, v254, 41
	s_mul_i32 s0, s0, s1
	v_readlane_b32 s1, v254, 40
	s_add_i32 s0, s0, s1
	s_ashr_i32 s1, s0, 31
	s_lshr_b32 s1, s1, 26
	s_add_i32 s1, s0, s1
	s_ashr_i32 s26, s1, 6
	s_lshl_b32 s26, s26, 3
	s_sub_i32 s27, s41, s26
	s_min_i32 s27, s27, 8
	s_abs_i32 s27, s27
	v_cvt_f32_u32_e32 v4, s27
	s_sub_i32 s28, 0, s27
	s_andn2_b32 s1, s1, 63
	s_sub_i32 s0, s0, s1
	v_rcp_iflag_f32_e32 v4, v4
	s_ashr_i32 s1, s0, 31
	s_abs_i32 s0, s0
	v_mul_f32_e32 v4, 0x4f7ffffe, v4
	v_cvt_u32_f32_e32 v4, v4
	s_nop 0
	v_readfirstlane_b32 s29, v4
	s_mul_i32 s28, s28, s29
	s_mul_hi_u32 s28, s29, s28
	s_add_i32 s29, s29, s28
	s_mul_hi_u32 s28, s0, s29
	s_mul_i32 s28, s28, s27
	s_sub_i32 s0, s0, s28
	s_sub_i32 s28, s0, s27
	s_cmp_ge_u32 s0, s27
	s_cselect_b32 s0, s28, s0
	s_sub_i32 s28, s0, s27
	s_cmp_ge_u32 s0, s27
	s_cselect_b32 s0, s28, s0
	s_xor_b32 s0, s0, s1
	s_sub_i32 s0, s0, s1
	s_add_i32 s1, s26, s38
	s_add_i32 s1, s1, s0
	v_lshl_add_u32 v4, s1, 8, v2
	v_ashrrev_i32_e32 v5, 31, v4
	v_lshl_add_u64 v[4:5], v[4:5], 2, s[16:17]
	global_load_dword v39, v[4:5], off
.LBB0_643:
	s_or_b64 exec, exec, s[24:25]
	v_readlane_b32 s0, v254, 48
	v_mov_b64_e32 v[4:5], s[22:23]
	v_readlane_b32 s1, v254, 49
	s_nop 1
	v_cmp_ge_i64_e32 vcc, s[0:1], v[4:5]
	s_cbranch_vccnz .LBB0_673
	s_and_saveexec_b64 s[24:25], s[10:11]
	s_cbranch_execz .LBB0_646
	v_readlane_b32 s0, v254, 47
	s_or_b32 s0, s41, s0
	v_readlane_b32 s1, v254, 46
	s_mul_i32 s0, s0, s1
	v_readlane_b32 s1, v254, 45
	s_add_i32 s0, s0, s1
	s_ashr_i32 s1, s0, 31
	s_lshr_b32 s1, s1, 26
	s_add_i32 s1, s0, s1
	s_ashr_i32 s26, s1, 6
	s_lshl_b32 s26, s26, 3
	s_sub_i32 s27, s41, s26
	s_min_i32 s27, s27, 8
	s_abs_i32 s27, s27
	v_cvt_f32_u32_e32 v4, s27
	s_sub_i32 s28, 0, s27
	s_andn2_b32 s1, s1, 63
	s_sub_i32 s0, s0, s1
	v_rcp_iflag_f32_e32 v4, v4
	s_ashr_i32 s1, s0, 31
	s_abs_i32 s0, s0
	v_mul_f32_e32 v4, 0x4f7ffffe, v4
	v_cvt_u32_f32_e32 v4, v4
	s_nop 0
	v_readfirstlane_b32 s29, v4
	s_mul_i32 s28, s28, s29
	s_mul_hi_u32 s28, s29, s28
	s_add_i32 s29, s29, s28
	s_mul_hi_u32 s28, s0, s29
	s_mul_i32 s28, s28, s27
	s_sub_i32 s0, s0, s28
	s_sub_i32 s28, s0, s27
	s_cmp_ge_u32 s0, s27
	s_cselect_b32 s0, s28, s0
	s_sub_i32 s28, s0, s27
	s_cmp_ge_u32 s0, s27
	s_cselect_b32 s0, s28, s0
	s_xor_b32 s0, s0, s1
	s_sub_i32 s0, s0, s1
	s_add_i32 s1, s26, s38
	s_add_i32 s1, s1, s0
	v_lshl_add_u32 v4, s1, 8, v2
	v_ashrrev_i32_e32 v5, 31, v4
	v_lshl_add_u64 v[4:5], v[4:5], 2, s[16:17]
	global_load_dword v40, v[4:5], off
.LBB0_646:
	s_or_b64 exec, exec, s[24:25]
	v_readlane_b32 s0, v254, 53
	v_mov_b64_e32 v[4:5], s[22:23]
	v_readlane_b32 s1, v254, 54
	s_nop 1
	v_cmp_ge_i64_e32 vcc, s[0:1], v[4:5]
	s_cbranch_vccnz .LBB0_673
	s_and_saveexec_b64 s[24:25], s[10:11]
	s_cbranch_execz .LBB0_649
	v_readlane_b32 s0, v254, 52
	s_or_b32 s0, s41, s0
	v_readlane_b32 s1, v254, 51
	s_mul_i32 s0, s0, s1
	v_readlane_b32 s1, v254, 50
	s_add_i32 s0, s0, s1
	s_ashr_i32 s1, s0, 31
	s_lshr_b32 s1, s1, 26
	s_add_i32 s1, s0, s1
	s_ashr_i32 s26, s1, 6
	s_lshl_b32 s26, s26, 3
	s_sub_i32 s27, s41, s26
	s_min_i32 s27, s27, 8
	s_abs_i32 s27, s27
	v_cvt_f32_u32_e32 v4, s27
	s_sub_i32 s28, 0, s27
	s_andn2_b32 s1, s1, 63
	s_sub_i32 s0, s0, s1
	v_rcp_iflag_f32_e32 v4, v4
	s_ashr_i32 s1, s0, 31
	s_abs_i32 s0, s0
	v_mul_f32_e32 v4, 0x4f7ffffe, v4
	v_cvt_u32_f32_e32 v4, v4
	s_nop 0
	v_readfirstlane_b32 s29, v4
	s_mul_i32 s28, s28, s29
	s_mul_hi_u32 s28, s29, s28
	s_add_i32 s29, s29, s28
	s_mul_hi_u32 s28, s0, s29
	s_mul_i32 s28, s28, s27
	s_sub_i32 s0, s0, s28
	s_sub_i32 s28, s0, s27
	s_cmp_ge_u32 s0, s27
	s_cselect_b32 s0, s28, s0
	s_sub_i32 s28, s0, s27
	s_cmp_ge_u32 s0, s27
	s_cselect_b32 s0, s28, s0
	s_xor_b32 s0, s0, s1
	s_sub_i32 s0, s0, s1
	s_add_i32 s1, s26, s38
	s_add_i32 s1, s1, s0
	v_lshl_add_u32 v4, s1, 8, v2
	v_ashrrev_i32_e32 v5, 31, v4
	v_lshl_add_u64 v[4:5], v[4:5], 2, s[16:17]
	global_load_dword v41, v[4:5], off
.LBB0_649:
	s_or_b64 exec, exec, s[24:25]
	v_readlane_b32 s0, v254, 58
	v_mov_b64_e32 v[4:5], s[22:23]
	v_readlane_b32 s1, v254, 59
	s_nop 1
	v_cmp_ge_i64_e32 vcc, s[0:1], v[4:5]
	s_cbranch_vccnz .LBB0_673
	s_and_saveexec_b64 s[24:25], s[10:11]
	s_cbranch_execz .LBB0_652
	v_readlane_b32 s0, v254, 57
	s_or_b32 s0, s41, s0
	v_readlane_b32 s1, v254, 56
	s_mul_i32 s0, s0, s1
	v_readlane_b32 s1, v254, 55
	s_add_i32 s0, s0, s1
	s_ashr_i32 s1, s0, 31
	s_lshr_b32 s1, s1, 26
	s_add_i32 s1, s0, s1
	s_ashr_i32 s26, s1, 6
	s_lshl_b32 s26, s26, 3
	s_sub_i32 s27, s41, s26
	s_min_i32 s27, s27, 8
	s_abs_i32 s27, s27
	v_cvt_f32_u32_e32 v4, s27
	s_sub_i32 s28, 0, s27
	s_andn2_b32 s1, s1, 63
	s_sub_i32 s0, s0, s1
	v_rcp_iflag_f32_e32 v4, v4
	s_ashr_i32 s1, s0, 31
	s_abs_i32 s0, s0
	v_mul_f32_e32 v4, 0x4f7ffffe, v4
	v_cvt_u32_f32_e32 v4, v4
	s_nop 0
	v_readfirstlane_b32 s29, v4
	s_mul_i32 s28, s28, s29
	s_mul_hi_u32 s28, s29, s28
	s_add_i32 s29, s29, s28
	s_mul_hi_u32 s28, s0, s29
	s_mul_i32 s28, s28, s27
	s_sub_i32 s0, s0, s28
	s_sub_i32 s28, s0, s27
	s_cmp_ge_u32 s0, s27
	s_cselect_b32 s0, s28, s0
	s_sub_i32 s28, s0, s27
	s_cmp_ge_u32 s0, s27
	s_cselect_b32 s0, s28, s0
	s_xor_b32 s0, s0, s1
	s_sub_i32 s0, s0, s1
	s_add_i32 s1, s26, s38
	s_add_i32 s1, s1, s0
	v_lshl_add_u32 v4, s1, 8, v2
	v_ashrrev_i32_e32 v5, 31, v4
	v_lshl_add_u64 v[4:5], v[4:5], 2, s[16:17]
	global_load_dword v42, v[4:5], off
.LBB0_652:
	s_or_b64 exec, exec, s[24:25]
	v_readlane_b32 s0, v254, 63
	v_mov_b64_e32 v[4:5], s[22:23]
	v_readlane_b32 s1, v253, 0
	s_nop 1
	v_cmp_ge_i64_e32 vcc, s[0:1], v[4:5]
	s_cbranch_vccnz .LBB0_673
	s_and_saveexec_b64 s[24:25], s[10:11]
	s_cbranch_execz .LBB0_655
	v_readlane_b32 s0, v254, 62
	s_or_b32 s0, s41, s0
	v_readlane_b32 s1, v254, 61
	s_mul_i32 s0, s0, s1
	v_readlane_b32 s1, v254, 60
	s_add_i32 s0, s0, s1
	s_ashr_i32 s1, s0, 31
	s_lshr_b32 s1, s1, 26
	s_add_i32 s1, s0, s1
	s_ashr_i32 s26, s1, 6
	s_lshl_b32 s26, s26, 3
	s_sub_i32 s27, s41, s26
	s_min_i32 s27, s27, 8
	s_abs_i32 s27, s27
	v_cvt_f32_u32_e32 v4, s27
	s_sub_i32 s28, 0, s27
	s_andn2_b32 s1, s1, 63
	s_sub_i32 s0, s0, s1
	v_rcp_iflag_f32_e32 v4, v4
	s_ashr_i32 s1, s0, 31
	s_abs_i32 s0, s0
	v_mul_f32_e32 v4, 0x4f7ffffe, v4
	v_cvt_u32_f32_e32 v4, v4
	s_nop 0
	v_readfirstlane_b32 s29, v4
	s_mul_i32 s28, s28, s29
	s_mul_hi_u32 s28, s29, s28
	s_add_i32 s29, s29, s28
	s_mul_hi_u32 s28, s0, s29
	s_mul_i32 s28, s28, s27
	s_sub_i32 s0, s0, s28
	s_sub_i32 s28, s0, s27
	s_cmp_ge_u32 s0, s27
	s_cselect_b32 s0, s28, s0
	s_sub_i32 s28, s0, s27
	s_cmp_ge_u32 s0, s27
	s_cselect_b32 s0, s28, s0
	s_xor_b32 s0, s0, s1
	s_sub_i32 s0, s0, s1
	s_add_i32 s1, s26, s38
	s_add_i32 s1, s1, s0
	v_lshl_add_u32 v4, s1, 8, v2
	v_ashrrev_i32_e32 v5, 31, v4
	v_lshl_add_u64 v[4:5], v[4:5], 2, s[16:17]
	global_load_dword v43, v[4:5], off
.LBB0_655:
	s_or_b64 exec, exec, s[24:25]
	v_readlane_b32 s0, v253, 4
	v_mov_b64_e32 v[4:5], s[22:23]
	v_readlane_b32 s1, v253, 5
	s_nop 1
	v_cmp_ge_i64_e32 vcc, s[0:1], v[4:5]
	s_cbranch_vccnz .LBB0_673
	s_and_saveexec_b64 s[24:25], s[10:11]
	s_cbranch_execz .LBB0_658
	v_readlane_b32 s0, v253, 3
	s_or_b32 s0, s41, s0
	v_readlane_b32 s1, v253, 2
	s_mul_i32 s0, s0, s1
	v_readlane_b32 s1, v253, 1
	s_add_i32 s0, s0, s1
	s_ashr_i32 s1, s0, 31
	s_lshr_b32 s1, s1, 26
	s_add_i32 s1, s0, s1
	s_ashr_i32 s26, s1, 6
	s_lshl_b32 s26, s26, 3
	s_sub_i32 s27, s41, s26
	s_min_i32 s27, s27, 8
	s_abs_i32 s27, s27
	v_cvt_f32_u32_e32 v4, s27
	s_sub_i32 s28, 0, s27
	s_andn2_b32 s1, s1, 63
	s_sub_i32 s0, s0, s1
	v_rcp_iflag_f32_e32 v4, v4
	s_ashr_i32 s1, s0, 31
	s_abs_i32 s0, s0
	v_mul_f32_e32 v4, 0x4f7ffffe, v4
	v_cvt_u32_f32_e32 v4, v4
	s_nop 0
	v_readfirstlane_b32 s29, v4
	s_mul_i32 s28, s28, s29
	s_mul_hi_u32 s28, s29, s28
	s_add_i32 s29, s29, s28
	s_mul_hi_u32 s28, s0, s29
	s_mul_i32 s28, s28, s27
	s_sub_i32 s0, s0, s28
	s_sub_i32 s28, s0, s27
	s_cmp_ge_u32 s0, s27
	s_cselect_b32 s0, s28, s0
	s_sub_i32 s28, s0, s27
	s_cmp_ge_u32 s0, s27
	s_cselect_b32 s0, s28, s0
	s_xor_b32 s0, s0, s1
	s_sub_i32 s0, s0, s1
	s_add_i32 s1, s26, s38
	s_add_i32 s1, s1, s0
	v_lshl_add_u32 v4, s1, 8, v2
	v_ashrrev_i32_e32 v5, 31, v4
	v_lshl_add_u64 v[4:5], v[4:5], 2, s[16:17]
	global_load_dword v44, v[4:5], off
.LBB0_658:
	s_or_b64 exec, exec, s[24:25]
	v_readlane_b32 s0, v253, 9
	v_mov_b64_e32 v[4:5], s[22:23]
	v_readlane_b32 s1, v253, 10
	s_nop 1
	v_cmp_ge_i64_e32 vcc, s[0:1], v[4:5]
	s_cbranch_vccnz .LBB0_673
	s_and_saveexec_b64 s[24:25], s[10:11]
	s_cbranch_execz .LBB0_661
	v_readlane_b32 s0, v253, 8
	s_or_b32 s0, s41, s0
	v_readlane_b32 s1, v253, 7
	s_mul_i32 s0, s0, s1
	v_readlane_b32 s1, v253, 6
	s_add_i32 s0, s0, s1
	s_ashr_i32 s1, s0, 31
	s_lshr_b32 s1, s1, 26
	s_add_i32 s1, s0, s1
	s_ashr_i32 s26, s1, 6
	s_lshl_b32 s26, s26, 3
	s_sub_i32 s27, s41, s26
	s_min_i32 s27, s27, 8
	s_abs_i32 s27, s27
	v_cvt_f32_u32_e32 v4, s27
	s_sub_i32 s28, 0, s27
	s_andn2_b32 s1, s1, 63
	s_sub_i32 s0, s0, s1
	v_rcp_iflag_f32_e32 v4, v4
	s_ashr_i32 s1, s0, 31
	s_abs_i32 s0, s0
	v_mul_f32_e32 v4, 0x4f7ffffe, v4
	v_cvt_u32_f32_e32 v4, v4
	s_nop 0
	v_readfirstlane_b32 s29, v4
	s_mul_i32 s28, s28, s29
	s_mul_hi_u32 s28, s29, s28
	s_add_i32 s29, s29, s28
	s_mul_hi_u32 s28, s0, s29
	s_mul_i32 s28, s28, s27
	s_sub_i32 s0, s0, s28
	s_sub_i32 s28, s0, s27
	s_cmp_ge_u32 s0, s27
	s_cselect_b32 s0, s28, s0
	s_sub_i32 s28, s0, s27
	s_cmp_ge_u32 s0, s27
	s_cselect_b32 s0, s28, s0
	s_xor_b32 s0, s0, s1
	s_sub_i32 s0, s0, s1
	s_add_i32 s1, s26, s38
	s_add_i32 s1, s1, s0
	v_lshl_add_u32 v4, s1, 8, v2
	v_ashrrev_i32_e32 v5, 31, v4
	v_lshl_add_u64 v[4:5], v[4:5], 2, s[16:17]
	global_load_dword v45, v[4:5], off
.LBB0_661:
	s_or_b64 exec, exec, s[24:25]
	v_readlane_b32 s0, v253, 14
	v_mov_b64_e32 v[4:5], s[22:23]
	v_readlane_b32 s1, v253, 15
	s_nop 1
	v_cmp_ge_i64_e32 vcc, s[0:1], v[4:5]
	s_cbranch_vccnz .LBB0_673
	s_and_saveexec_b64 s[24:25], s[10:11]
	s_cbranch_execz .LBB0_664
	v_readlane_b32 s0, v253, 13
	s_or_b32 s0, s41, s0
	v_readlane_b32 s1, v253, 12
	s_mul_i32 s0, s0, s1
	v_readlane_b32 s1, v253, 11
	s_add_i32 s0, s0, s1
	s_ashr_i32 s1, s0, 31
	s_lshr_b32 s1, s1, 26
	s_add_i32 s1, s0, s1
	s_ashr_i32 s26, s1, 6
	s_lshl_b32 s26, s26, 3
	s_sub_i32 s27, s41, s26
	s_min_i32 s27, s27, 8
	s_abs_i32 s27, s27
	v_cvt_f32_u32_e32 v4, s27
	s_sub_i32 s28, 0, s27
	s_andn2_b32 s1, s1, 63
	s_sub_i32 s0, s0, s1
	v_rcp_iflag_f32_e32 v4, v4
	s_ashr_i32 s1, s0, 31
	s_abs_i32 s0, s0
	v_mul_f32_e32 v4, 0x4f7ffffe, v4
	v_cvt_u32_f32_e32 v4, v4
	s_nop 0
	v_readfirstlane_b32 s29, v4
	s_mul_i32 s28, s28, s29
	s_mul_hi_u32 s28, s29, s28
	s_add_i32 s29, s29, s28
	s_mul_hi_u32 s28, s0, s29
	s_mul_i32 s28, s28, s27
	s_sub_i32 s0, s0, s28
	s_sub_i32 s28, s0, s27
	s_cmp_ge_u32 s0, s27
	s_cselect_b32 s0, s28, s0
	s_sub_i32 s28, s0, s27
	s_cmp_ge_u32 s0, s27
	s_cselect_b32 s0, s28, s0
	s_xor_b32 s0, s0, s1
	s_sub_i32 s0, s0, s1
	s_add_i32 s1, s26, s38
	s_add_i32 s1, s1, s0
	v_lshl_add_u32 v4, s1, 8, v2
	v_ashrrev_i32_e32 v5, 31, v4
	v_lshl_add_u64 v[4:5], v[4:5], 2, s[16:17]
	global_load_dword v46, v[4:5], off
.LBB0_664:
	s_or_b64 exec, exec, s[24:25]
	v_readlane_b32 s0, v253, 19
	v_mov_b64_e32 v[4:5], s[22:23]
	v_readlane_b32 s1, v253, 20
	s_nop 1
	v_cmp_ge_i64_e32 vcc, s[0:1], v[4:5]
	s_cbranch_vccnz .LBB0_673
	s_and_saveexec_b64 s[24:25], s[10:11]
	s_cbranch_execz .LBB0_667
	v_readlane_b32 s0, v253, 18
	s_or_b32 s0, s41, s0
	v_readlane_b32 s1, v253, 17
	s_mul_i32 s0, s0, s1
	v_readlane_b32 s1, v253, 16
	s_add_i32 s0, s0, s1
	s_ashr_i32 s1, s0, 31
	s_lshr_b32 s1, s1, 26
	s_add_i32 s1, s0, s1
	s_ashr_i32 s26, s1, 6
	s_lshl_b32 s26, s26, 3
	s_sub_i32 s27, s41, s26
	s_min_i32 s27, s27, 8
	s_abs_i32 s27, s27
	v_cvt_f32_u32_e32 v4, s27
	s_sub_i32 s28, 0, s27
	s_andn2_b32 s1, s1, 63
	s_sub_i32 s0, s0, s1
	v_rcp_iflag_f32_e32 v4, v4
	s_ashr_i32 s1, s0, 31
	s_abs_i32 s0, s0
	v_mul_f32_e32 v4, 0x4f7ffffe, v4
	v_cvt_u32_f32_e32 v4, v4
	s_nop 0
	v_readfirstlane_b32 s29, v4
	s_mul_i32 s28, s28, s29
	s_mul_hi_u32 s28, s29, s28
	s_add_i32 s29, s29, s28
	s_mul_hi_u32 s28, s0, s29
	s_mul_i32 s28, s28, s27
	s_sub_i32 s0, s0, s28
	s_sub_i32 s28, s0, s27
	s_cmp_ge_u32 s0, s27
	s_cselect_b32 s0, s28, s0
	s_sub_i32 s28, s0, s27
	s_cmp_ge_u32 s0, s27
	s_cselect_b32 s0, s28, s0
	s_xor_b32 s0, s0, s1
	s_sub_i32 s0, s0, s1
	s_add_i32 s1, s26, s38
	s_add_i32 s1, s1, s0
	v_lshl_add_u32 v4, s1, 8, v2
	v_ashrrev_i32_e32 v5, 31, v4
	v_lshl_add_u64 v[4:5], v[4:5], 2, s[16:17]
	global_load_dword v47, v[4:5], off
.LBB0_667:
	s_or_b64 exec, exec, s[24:25]
	v_readlane_b32 s0, v253, 24
	v_mov_b64_e32 v[4:5], s[22:23]
	v_readlane_b32 s1, v253, 25
	s_nop 1
	v_cmp_ge_i64_e32 vcc, s[0:1], v[4:5]
	s_cbranch_vccnz .LBB0_673
	s_and_saveexec_b64 s[24:25], s[10:11]
	s_cbranch_execz .LBB0_670
	v_readlane_b32 s0, v253, 23
	s_or_b32 s0, s41, s0
	v_readlane_b32 s1, v253, 22
	s_mul_i32 s0, s0, s1
	v_readlane_b32 s1, v253, 21
	s_add_i32 s0, s0, s1
	s_ashr_i32 s1, s0, 31
	s_lshr_b32 s1, s1, 26
	s_add_i32 s1, s0, s1
	s_ashr_i32 s10, s1, 6
	s_lshl_b32 s10, s10, 3
	s_sub_i32 s11, s41, s10
	s_min_i32 s11, s11, 8
	s_abs_i32 s11, s11
	v_cvt_f32_u32_e32 v4, s11
	s_sub_i32 s26, 0, s11
	s_andn2_b32 s1, s1, 63
	s_sub_i32 s0, s0, s1
	v_rcp_iflag_f32_e32 v4, v4
	s_ashr_i32 s1, s0, 31
	s_abs_i32 s0, s0
	v_mul_f32_e32 v4, 0x4f7ffffe, v4
	v_cvt_u32_f32_e32 v4, v4
	s_nop 0
	v_readfirstlane_b32 s27, v4
	s_mul_i32 s26, s26, s27
	s_mul_hi_u32 s26, s27, s26
	s_add_i32 s27, s27, s26
	s_mul_hi_u32 s26, s0, s27
	s_mul_i32 s26, s26, s11
	s_sub_i32 s0, s0, s26
	s_sub_i32 s26, s0, s11
	s_cmp_ge_u32 s0, s11
	s_cselect_b32 s0, s26, s0
	s_sub_i32 s26, s0, s11
	s_cmp_ge_u32 s0, s11
	s_cselect_b32 s0, s26, s0
	s_xor_b32 s0, s0, s1
	s_sub_i32 s0, s0, s1
	s_add_i32 s1, s10, s38
	s_add_i32 s1, s1, s0
	v_lshl_add_u32 v4, s1, 8, v2
	v_ashrrev_i32_e32 v5, 31, v4
	v_lshl_add_u64 v[4:5], v[4:5], 2, s[16:17]
	global_load_dword v48, v[4:5], off
.LBB0_670:
	s_or_b64 exec, exec, s[24:25]
	v_readlane_b32 s0, v253, 27
	v_mov_b64_e32 v[4:5], s[22:23]
	v_readlane_b32 s1, v253, 28
	s_nop 1
	v_cmp_lt_i64_e32 vcc, s[0:1], v[4:5]
	s_xor_b64 s[0:1], s[8:9], -1
	s_and_b64 s[0:1], vcc, s[0:1]
	s_and_saveexec_b64 s[8:9], s[0:1]
	s_cbranch_execz .LBB0_672
	v_readlane_b32 s0, v253, 30
	s_or_b32 s0, s41, s0
	v_readlane_b32 s1, v253, 29
	s_mul_i32 s0, s0, s1
	v_readlane_b32 s1, v253, 26
	s_add_i32 s0, s0, s1
	s_ashr_i32 s1, s0, 31
	s_lshr_b32 s1, s1, 26
	s_add_i32 s1, s0, s1
	s_ashr_i32 s10, s1, 6
	s_lshl_b32 s10, s10, 3
	s_sub_i32 s11, s41, s10
	s_min_i32 s11, s11, 8
	s_abs_i32 s11, s11
	v_cvt_f32_u32_e32 v4, s11
	s_sub_i32 s24, 0, s11
	s_andn2_b32 s1, s1, 63
	s_sub_i32 s0, s0, s1
	v_rcp_iflag_f32_e32 v4, v4
	s_ashr_i32 s1, s0, 31
	s_abs_i32 s0, s0
	v_mul_f32_e32 v4, 0x4f7ffffe, v4
	v_cvt_u32_f32_e32 v4, v4
	s_nop 0
	v_readfirstlane_b32 s25, v4
	s_mul_i32 s24, s24, s25
	s_mul_hi_u32 s24, s25, s24
	s_add_i32 s25, s25, s24
	s_mul_hi_u32 s24, s0, s25
	s_mul_i32 s24, s24, s11
	s_sub_i32 s0, s0, s24
	s_sub_i32 s24, s0, s11
	s_cmp_ge_u32 s0, s11
	s_cselect_b32 s0, s24, s0
	s_sub_i32 s24, s0, s11
	s_cmp_ge_u32 s0, s11
	s_cselect_b32 s0, s24, s0
	s_xor_b32 s0, s0, s1
	s_sub_i32 s0, s0, s1
	s_add_i32 s1, s10, s38
	s_add_i32 s1, s1, s0
	v_lshl_add_u32 v4, s1, 8, v2
	v_ashrrev_i32_e32 v5, 31, v4
	v_lshl_add_u64 v[4:5], v[4:5], 2, s[16:17]
	global_load_dword v49, v[4:5], off

.LBB0_673:
	s_waitcnt vmcnt(0)
	v_cmp_gt_u32_e32 vcc, 0x100, v2
	s_mov_b64 exec, vcc
	v_lshlrev_b32_e32 v34, 10, v34
	v_lshlrev_b32_e32 v35, 10, v35
	v_lshlrev_b32_e32 v36, 10, v36
	v_lshlrev_b32_e32 v37, 10, v37
	v_lshlrev_b32_e32 v38, 10, v38
	v_lshlrev_b32_e32 v39, 10, v39
	v_lshlrev_b32_e32 v40, 10, v40
	v_lshlrev_b32_e32 v41, 10, v41
	v_lshlrev_b32_e32 v42, 10, v42
	v_lshlrev_b32_e32 v43, 10, v43
	v_lshlrev_b32_e32 v44, 10, v44
	v_lshlrev_b32_e32 v45, 10, v45
	v_lshlrev_b32_e32 v46, 10, v46
	v_lshlrev_b32_e32 v47, 10, v47
	v_lshlrev_b32_e32 v48, 10, v48
	v_lshlrev_b32_e32 v49, 10, v49
	ds_write_b32 v3, v34
	ds_write_b32 v3, v35 offset:1024
	ds_write_b32 v3, v36 offset:2048
	ds_write_b32 v3, v37 offset:3072
	ds_write_b32 v3, v38 offset:4096
	ds_write_b32 v3, v39 offset:5120
	ds_write_b32 v3, v40 offset:6144
	ds_write_b32 v3, v41 offset:7168
	ds_write_b32 v3, v42 offset:8192
	ds_write_b32 v3, v43 offset:9216
	ds_write_b32 v3, v44 offset:10240
	ds_write_b32 v3, v45 offset:11264
	ds_write_b32 v3, v46 offset:12288
	ds_write_b32 v3, v47 offset:13312
	ds_write_b32 v3, v48 offset:14336
	ds_write_b32 v3, v49 offset:15360
	s_mov_b64 exec, -1

.LBB0_1239:
	s_sub_i32 s0, 0x200, s10
	s_min_i32 s41, s0, s90
	s_lshl_b32 s24, s41, 3
	s_ashr_i32 s25, s24, 31
	v_mov_b32_e32 v2, v0
	s_cmp_lt_i32 s2, s24
	s_cselect_b64 s[14:15], -1, 0
	s_cmp_ge_i32 s2, s24
	v_readfirstlane_b32 s42, v2
	s_cbranch_scc1 .Lgidx_skip_1
	s_movk_i32 s0, 0xff
	v_cmp_lt_i32_e64 s[8:9], s0, v2
	s_movk_i32 s0, 0x100
	v_lshl_add_u32 v3, v2, 2, s95
	v_cmp_gt_i32_e64 s[12:13], s0, v2
	s_and_saveexec_b64 s[26:27], s[12:13]
	s_cbranch_execz .LBB0_1242
	s_or_b32 s0, s41, s80
	s_mul_i32 s0, s0, s76
	s_add_i32 s0, s0, s91
	s_ashr_i32 s1, s0, 31
	s_lshr_b32 s1, s1, 26
	s_add_i32 s1, s0, s1
	s_ashr_i32 s28, s1, 6
	s_lshl_b32 s28, s28, 3
	s_sub_i32 s29, s41, s28
	s_min_i32 s29, s29, 8
	s_abs_i32 s29, s29
	v_cvt_f32_u32_e32 v4, s29
	s_sub_i32 s30, 0, s29
	s_andn2_b32 s1, s1, 63
	s_sub_i32 s0, s0, s1
	v_rcp_iflag_f32_e32 v4, v4
	s_ashr_i32 s1, s0, 31
	s_abs_i32 s0, s0
	v_mul_f32_e32 v4, 0x4f7ffffe, v4
	v_cvt_u32_f32_e32 v4, v4
	s_nop 0
	v_readfirstlane_b32 s31, v4
	s_mul_i32 s30, s30, s31
	s_mul_hi_u32 s30, s31, s30
	s_add_i32 s31, s31, s30
	s_mul_hi_u32 s30, s0, s31
	s_mul_i32 s30, s30, s29
	s_sub_i32 s0, s0, s30
	s_sub_i32 s30, s0, s29
	s_cmp_ge_u32 s0, s29
	s_cselect_b32 s0, s30, s0
	s_sub_i32 s30, s0, s29
	s_cmp_ge_u32 s0, s29
	s_cselect_b32 s0, s30, s0
	s_xor_b32 s0, s0, s1
	s_sub_i32 s0, s0, s1
	s_add_i32 s1, s28, s10
	s_add_i32 s1, s1, s0
	v_lshl_add_u32 v4, s1, 8, v2
	v_ashrrev_i32_e32 v5, 31, v4
	v_lshl_add_u64 v[4:5], v[4:5], 2, s[18:19]
	global_load_dword v34, v[4:5], off
.LBB0_1242:
	s_or_b64 exec, exec, s[26:27]
	v_readlane_b32 s0, v254, 23
	v_mov_b64_e32 v[4:5], s[24:25]
	v_readlane_b32 s1, v254, 24
	s_nop 1
	v_cmp_ge_i64_e32 vcc, s[0:1], v[4:5]
	s_cbranch_vccnz .LBB0_1287
	s_and_saveexec_b64 s[26:27], s[12:13]
	s_cbranch_execz .LBB0_1245
	v_readlane_b32 s0, v254, 22
	s_or_b32 s0, s41, s0
	v_readlane_b32 s1, v254, 21
	s_mul_i32 s0, s0, s1
	s_add_i32 s0, s0, s89
	s_ashr_i32 s1, s0, 31
	s_lshr_b32 s1, s1, 26
	s_add_i32 s1, s0, s1
	s_ashr_i32 s28, s1, 6
	s_lshl_b32 s28, s28, 3
	s_sub_i32 s29, s41, s28
	s_min_i32 s29, s29, 8
	s_abs_i32 s29, s29
	v_cvt_f32_u32_e32 v4, s29
	s_sub_i32 s30, 0, s29
	s_andn2_b32 s1, s1, 63
	s_sub_i32 s0, s0, s1
	v_rcp_iflag_f32_e32 v4, v4
	s_ashr_i32 s1, s0, 31
	s_abs_i32 s0, s0
	v_mul_f32_e32 v4, 0x4f7ffffe, v4
	v_cvt_u32_f32_e32 v4, v4
	s_nop 0
	v_readfirstlane_b32 s31, v4
	s_mul_i32 s30, s30, s31
	s_mul_hi_u32 s30, s31, s30
	s_add_i32 s31, s31, s30
	s_mul_hi_u32 s30, s0, s31
	s_mul_i32 s30, s30, s29
	s_sub_i32 s0, s0, s30
	s_sub_i32 s30, s0, s29
	s_cmp_ge_u32 s0, s29
	s_cselect_b32 s0, s30, s0
	s_sub_i32 s30, s0, s29
	s_cmp_ge_u32 s0, s29
	s_cselect_b32 s0, s30, s0
	s_xor_b32 s0, s0, s1
	s_sub_i32 s0, s0, s1
	s_add_i32 s1, s28, s10
	s_add_i32 s1, s1, s0
	v_lshl_add_u32 v4, s1, 8, v2
	v_ashrrev_i32_e32 v5, 31, v4
	v_lshl_add_u64 v[4:5], v[4:5], 2, s[18:19]
	global_load_dword v35, v[4:5], off
.LBB0_1245:
	s_or_b64 exec, exec, s[26:27]
	v_readlane_b32 s0, v254, 28
	v_mov_b64_e32 v[4:5], s[24:25]
	v_readlane_b32 s1, v254, 29
	s_nop 1
	v_cmp_ge_i64_e32 vcc, s[0:1], v[4:5]
	s_cbranch_vccnz .LBB0_1287
	s_and_saveexec_b64 s[26:27], s[12:13]
	s_cbranch_execz .LBB0_1248
	v_readlane_b32 s0, v254, 27
	s_or_b32 s0, s41, s0
	v_readlane_b32 s1, v254, 26
	s_mul_i32 s0, s0, s1
	v_readlane_b32 s1, v254, 25
	s_add_i32 s0, s0, s1
	s_ashr_i32 s1, s0, 31
	s_lshr_b32 s1, s1, 26
	s_add_i32 s1, s0, s1
	s_ashr_i32 s28, s1, 6
	s_lshl_b32 s28, s28, 3
	s_sub_i32 s29, s41, s28
	s_min_i32 s29, s29, 8
	s_abs_i32 s29, s29
	v_cvt_f32_u32_e32 v4, s29
	s_sub_i32 s30, 0, s29
	s_andn2_b32 s1, s1, 63
	s_sub_i32 s0, s0, s1
	v_rcp_iflag_f32_e32 v4, v4
	s_ashr_i32 s1, s0, 31
	s_abs_i32 s0, s0
	v_mul_f32_e32 v4, 0x4f7ffffe, v4
	v_cvt_u32_f32_e32 v4, v4
	s_nop 0
	v_readfirstlane_b32 s31, v4
	s_mul_i32 s30, s30, s31
	s_mul_hi_u32 s30, s31, s30
	s_add_i32 s31, s31, s30
	s_mul_hi_u32 s30, s0, s31
	s_mul_i32 s30, s30, s29
	s_sub_i32 s0, s0, s30
	s_sub_i32 s30, s0, s29
	s_cmp_ge_u32 s0, s29
	s_cselect_b32 s0, s30, s0
	s_sub_i32 s30, s0, s29
	s_cmp_ge_u32 s0, s29
	s_cselect_b32 s0, s30, s0
	s_xor_b32 s0, s0, s1
	s_sub_i32 s0, s0, s1
	s_add_i32 s1, s28, s10
	s_add_i32 s1, s1, s0
	v_lshl_add_u32 v4, s1, 8, v2
	v_ashrrev_i32_e32 v5, 31, v4
	v_lshl_add_u64 v[4:5], v[4:5], 2, s[18:19]
	global_load_dword v36, v[4:5], off
.LBB0_1248:
	s_or_b64 exec, exec, s[26:27]
	v_readlane_b32 s0, v254, 33
	v_mov_b64_e32 v[4:5], s[24:25]
	v_readlane_b32 s1, v254, 34
	s_nop 1
	v_cmp_ge_i64_e32 vcc, s[0:1], v[4:5]
	s_cbranch_vccnz .LBB0_1287
	s_and_saveexec_b64 s[26:27], s[12:13]
	s_cbranch_execz .LBB0_1251
	v_readlane_b32 s0, v254, 32
	s_or_b32 s0, s41, s0
	v_readlane_b32 s1, v254, 31
	s_mul_i32 s0, s0, s1
	v_readlane_b32 s1, v254, 30
	s_add_i32 s0, s0, s1
	s_ashr_i32 s1, s0, 31
	s_lshr_b32 s1, s1, 26
	s_add_i32 s1, s0, s1
	s_ashr_i32 s28, s1, 6
	s_lshl_b32 s28, s28, 3
	s_sub_i32 s29, s41, s28
	s_min_i32 s29, s29, 8
	s_abs_i32 s29, s29
	v_cvt_f32_u32_e32 v4, s29
	s_sub_i32 s30, 0, s29
	s_andn2_b32 s1, s1, 63
	s_sub_i32 s0, s0, s1
	v_rcp_iflag_f32_e32 v4, v4
	s_ashr_i32 s1, s0, 31
	s_abs_i32 s0, s0
	v_mul_f32_e32 v4, 0x4f7ffffe, v4
	v_cvt_u32_f32_e32 v4, v4
	s_nop 0
	v_readfirstlane_b32 s31, v4
	s_mul_i32 s30, s30, s31
	s_mul_hi_u32 s30, s31, s30
	s_add_i32 s31, s31, s30
	s_mul_hi_u32 s30, s0, s31
	s_mul_i32 s30, s30, s29
	s_sub_i32 s0, s0, s30
	s_sub_i32 s30, s0, s29
	s_cmp_ge_u32 s0, s29
	s_cselect_b32 s0, s30, s0
	s_sub_i32 s30, s0, s29
	s_cmp_ge_u32 s0, s29
	s_cselect_b32 s0, s30, s0
	s_xor_b32 s0, s0, s1
	s_sub_i32 s0, s0, s1
	s_add_i32 s1, s28, s10
	s_add_i32 s1, s1, s0
	v_lshl_add_u32 v4, s1, 8, v2
	v_ashrrev_i32_e32 v5, 31, v4
	v_lshl_add_u64 v[4:5], v[4:5], 2, s[18:19]
	global_load_dword v37, v[4:5], off
.LBB0_1251:
	s_or_b64 exec, exec, s[26:27]
	v_readlane_b32 s0, v254, 38
	v_mov_b64_e32 v[4:5], s[24:25]
	v_readlane_b32 s1, v254, 39
	s_nop 1
	v_cmp_ge_i64_e32 vcc, s[0:1], v[4:5]
	s_cbranch_vccnz .LBB0_1287
	s_and_saveexec_b64 s[26:27], s[12:13]
	s_cbranch_execz .LBB0_1254
	v_readlane_b32 s0, v254, 37
	s_or_b32 s0, s41, s0
	v_readlane_b32 s1, v254, 36
	s_mul_i32 s0, s0, s1
	v_readlane_b32 s1, v254, 35
	s_add_i32 s0, s0, s1
	s_ashr_i32 s1, s0, 31
	s_lshr_b32 s1, s1, 26
	s_add_i32 s1, s0, s1
	s_ashr_i32 s28, s1, 6
	s_lshl_b32 s28, s28, 3
	s_sub_i32 s29, s41, s28
	s_min_i32 s29, s29, 8
	s_abs_i32 s29, s29
	v_cvt_f32_u32_e32 v4, s29
	s_sub_i32 s30, 0, s29
	s_andn2_b32 s1, s1, 63
	s_sub_i32 s0, s0, s1
	v_rcp_iflag_f32_e32 v4, v4
	s_ashr_i32 s1, s0, 31
	s_abs_i32 s0, s0
	v_mul_f32_e32 v4, 0x4f7ffffe, v4
	v_cvt_u32_f32_e32 v4, v4
	s_nop 0
	v_readfirstlane_b32 s31, v4
	s_mul_i32 s30, s30, s31
	s_mul_hi_u32 s30, s31, s30
	s_add_i32 s31, s31, s30
	s_mul_hi_u32 s30, s0, s31
	s_mul_i32 s30, s30, s29
	s_sub_i32 s0, s0, s30
	s_sub_i32 s30, s0, s29
	s_cmp_ge_u32 s0, s29
	s_cselect_b32 s0, s30, s0
	s_sub_i32 s30, s0, s29
	s_cmp_ge_u32 s0, s29
	s_cselect_b32 s0, s30, s0
	s_xor_b32 s0, s0, s1
	s_sub_i32 s0, s0, s1
	s_add_i32 s1, s28, s10
	s_add_i32 s1, s1, s0
	v_lshl_add_u32 v4, s1, 8, v2
	v_ashrrev_i32_e32 v5, 31, v4
	v_lshl_add_u64 v[4:5], v[4:5], 2, s[18:19]
	global_load_dword v38, v[4:5], off
.LBB0_1254:
	s_or_b64 exec, exec, s[26:27]
	v_readlane_b32 s0, v254, 43
	v_mov_b64_e32 v[4:5], s[24:25]
	v_readlane_b32 s1, v254, 44
	s_nop 1
	v_cmp_ge_i64_e32 vcc, s[0:1], v[4:5]
	s_cbranch_vccnz .LBB0_1287
	s_and_saveexec_b64 s[26:27], s[12:13]
	s_cbranch_execz .LBB0_1257
	v_readlane_b32 s0, v254, 42
	s_or_b32 s0, s41, s0
	v_readlane_b32 s1, v254, 41
	s_mul_i32 s0, s0, s1
	v_readlane_b32 s1, v254, 40
	s_add_i32 s0, s0, s1
	s_ashr_i32 s1, s0, 31
	s_lshr_b32 s1, s1, 26
	s_add_i32 s1, s0, s1
	s_ashr_i32 s28, s1, 6
	s_lshl_b32 s28, s28, 3
	s_sub_i32 s29, s41, s28
	s_min_i32 s29, s29, 8
	s_abs_i32 s29, s29
	v_cvt_f32_u32_e32 v4, s29
	s_sub_i32 s30, 0, s29
	s_andn2_b32 s1, s1, 63
	s_sub_i32 s0, s0, s1
	v_rcp_iflag_f32_e32 v4, v4
	s_ashr_i32 s1, s0, 31
	s_abs_i32 s0, s0
	v_mul_f32_e32 v4, 0x4f7ffffe, v4
	v_cvt_u32_f32_e32 v4, v4
	s_nop 0
	v_readfirstlane_b32 s31, v4
	s_mul_i32 s30, s30, s31
	s_mul_hi_u32 s30, s31, s30
	s_add_i32 s31, s31, s30
	s_mul_hi_u32 s30, s0, s31
	s_mul_i32 s30, s30, s29
	s_sub_i32 s0, s0, s30
	s_sub_i32 s30, s0, s29
	s_cmp_ge_u32 s0, s29
	s_cselect_b32 s0, s30, s0
	s_sub_i32 s30, s0, s29
	s_cmp_ge_u32 s0, s29
	s_cselect_b32 s0, s30, s0
	s_xor_b32 s0, s0, s1
	s_sub_i32 s0, s0, s1
	s_add_i32 s1, s28, s10
	s_add_i32 s1, s1, s0
	v_lshl_add_u32 v4, s1, 8, v2
	v_ashrrev_i32_e32 v5, 31, v4
	v_lshl_add_u64 v[4:5], v[4:5], 2, s[18:19]
	global_load_dword v39, v[4:5], off
.LBB0_1257:
	s_or_b64 exec, exec, s[26:27]
	v_readlane_b32 s0, v254, 48
	v_mov_b64_e32 v[4:5], s[24:25]
	v_readlane_b32 s1, v254, 49
	s_nop 1
	v_cmp_ge_i64_e32 vcc, s[0:1], v[4:5]
	s_cbranch_vccnz .LBB0_1287
	s_and_saveexec_b64 s[26:27], s[12:13]
	s_cbranch_execz .LBB0_1260
	v_readlane_b32 s0, v254, 47
	s_or_b32 s0, s41, s0
	v_readlane_b32 s1, v254, 46
	s_mul_i32 s0, s0, s1
	v_readlane_b32 s1, v254, 45
	s_add_i32 s0, s0, s1
	s_ashr_i32 s1, s0, 31
	s_lshr_b32 s1, s1, 26
	s_add_i32 s1, s0, s1
	s_ashr_i32 s28, s1, 6
	s_lshl_b32 s28, s28, 3
	s_sub_i32 s29, s41, s28
	s_min_i32 s29, s29, 8
	s_abs_i32 s29, s29
	v_cvt_f32_u32_e32 v4, s29
	s_sub_i32 s30, 0, s29
	s_andn2_b32 s1, s1, 63
	s_sub_i32 s0, s0, s1
	v_rcp_iflag_f32_e32 v4, v4
	s_ashr_i32 s1, s0, 31
	s_abs_i32 s0, s0
	v_mul_f32_e32 v4, 0x4f7ffffe, v4
	v_cvt_u32_f32_e32 v4, v4
	s_nop 0
	v_readfirstlane_b32 s31, v4
	s_mul_i32 s30, s30, s31
	s_mul_hi_u32 s30, s31, s30
	s_add_i32 s31, s31, s30
	s_mul_hi_u32 s30, s0, s31
	s_mul_i32 s30, s30, s29
	s_sub_i32 s0, s0, s30
	s_sub_i32 s30, s0, s29
	s_cmp_ge_u32 s0, s29
	s_cselect_b32 s0, s30, s0
	s_sub_i32 s30, s0, s29
	s_cmp_ge_u32 s0, s29
	s_cselect_b32 s0, s30, s0
	s_xor_b32 s0, s0, s1
	s_sub_i32 s0, s0, s1
	s_add_i32 s1, s28, s10
	s_add_i32 s1, s1, s0
	v_lshl_add_u32 v4, s1, 8, v2
	v_ashrrev_i32_e32 v5, 31, v4
	v_lshl_add_u64 v[4:5], v[4:5], 2, s[18:19]
	global_load_dword v40, v[4:5], off
.LBB0_1260:
	s_or_b64 exec, exec, s[26:27]
	v_readlane_b32 s0, v254, 53
	v_mov_b64_e32 v[4:5], s[24:25]
	v_readlane_b32 s1, v254, 54
	s_nop 1
	v_cmp_ge_i64_e32 vcc, s[0:1], v[4:5]
	s_cbranch_vccnz .LBB0_1287
	s_and_saveexec_b64 s[26:27], s[12:13]
	s_cbranch_execz .LBB0_1263
	v_readlane_b32 s0, v254, 52
	s_or_b32 s0, s41, s0
	v_readlane_b32 s1, v254, 51
	s_mul_i32 s0, s0, s1
	v_readlane_b32 s1, v254, 50
	s_add_i32 s0, s0, s1
	s_ashr_i32 s1, s0, 31
	s_lshr_b32 s1, s1, 26
	s_add_i32 s1, s0, s1
	s_ashr_i32 s28, s1, 6
	s_lshl_b32 s28, s28, 3
	s_sub_i32 s29, s41, s28
	s_min_i32 s29, s29, 8
	s_abs_i32 s29, s29
	v_cvt_f32_u32_e32 v4, s29
	s_sub_i32 s30, 0, s29
	s_andn2_b32 s1, s1, 63
	s_sub_i32 s0, s0, s1
	v_rcp_iflag_f32_e32 v4, v4
	s_ashr_i32 s1, s0, 31
	s_abs_i32 s0, s0
	v_mul_f32_e32 v4, 0x4f7ffffe, v4
	v_cvt_u32_f32_e32 v4, v4
	s_nop 0
	v_readfirstlane_b32 s31, v4
	s_mul_i32 s30, s30, s31
	s_mul_hi_u32 s30, s31, s30
	s_add_i32 s31, s31, s30
	s_mul_hi_u32 s30, s0, s31
	s_mul_i32 s30, s30, s29
	s_sub_i32 s0, s0, s30
	s_sub_i32 s30, s0, s29
	s_cmp_ge_u32 s0, s29
	s_cselect_b32 s0, s30, s0
	s_sub_i32 s30, s0, s29
	s_cmp_ge_u32 s0, s29
	s_cselect_b32 s0, s30, s0
	s_xor_b32 s0, s0, s1
	s_sub_i32 s0, s0, s1
	s_add_i32 s1, s28, s10
	s_add_i32 s1, s1, s0
	v_lshl_add_u32 v4, s1, 8, v2
	v_ashrrev_i32_e32 v5, 31, v4
	v_lshl_add_u64 v[4:5], v[4:5], 2, s[18:19]
	global_load_dword v41, v[4:5], off
.LBB0_1263:
	s_or_b64 exec, exec, s[26:27]
	v_readlane_b32 s0, v254, 58
	v_mov_b64_e32 v[4:5], s[24:25]
	v_readlane_b32 s1, v254, 59
	s_nop 1
	v_cmp_ge_i64_e32 vcc, s[0:1], v[4:5]
	s_cbranch_vccnz .LBB0_1287
	s_and_saveexec_b64 s[26:27], s[12:13]
	s_cbranch_execz .LBB0_1266
	v_readlane_b32 s0, v254, 57
	s_or_b32 s0, s41, s0
	v_readlane_b32 s1, v254, 56
	s_mul_i32 s0, s0, s1
	v_readlane_b32 s1, v254, 55
	s_add_i32 s0, s0, s1
	s_ashr_i32 s1, s0, 31
	s_lshr_b32 s1, s1, 26
	s_add_i32 s1, s0, s1
	s_ashr_i32 s28, s1, 6
	s_lshl_b32 s28, s28, 3
	s_sub_i32 s29, s41, s28
	s_min_i32 s29, s29, 8
	s_abs_i32 s29, s29
	v_cvt_f32_u32_e32 v4, s29
	s_sub_i32 s30, 0, s29
	s_andn2_b32 s1, s1, 63
	s_sub_i32 s0, s0, s1
	v_rcp_iflag_f32_e32 v4, v4
	s_ashr_i32 s1, s0, 31
	s_abs_i32 s0, s0
	v_mul_f32_e32 v4, 0x4f7ffffe, v4
	v_cvt_u32_f32_e32 v4, v4
	s_nop 0
	v_readfirstlane_b32 s31, v4
	s_mul_i32 s30, s30, s31
	s_mul_hi_u32 s30, s31, s30
	s_add_i32 s31, s31, s30
	s_mul_hi_u32 s30, s0, s31
	s_mul_i32 s30, s30, s29
	s_sub_i32 s0, s0, s30
	s_sub_i32 s30, s0, s29
	s_cmp_ge_u32 s0, s29
	s_cselect_b32 s0, s30, s0
	s_sub_i32 s30, s0, s29
	s_cmp_ge_u32 s0, s29
	s_cselect_b32 s0, s30, s0
	s_xor_b32 s0, s0, s1
	s_sub_i32 s0, s0, s1
	s_add_i32 s1, s28, s10
	s_add_i32 s1, s1, s0
	v_lshl_add_u32 v4, s1, 8, v2
	v_ashrrev_i32_e32 v5, 31, v4
	v_lshl_add_u64 v[4:5], v[4:5], 2, s[18:19]
	global_load_dword v42, v[4:5], off
.LBB0_1266:
	s_or_b64 exec, exec, s[26:27]
	v_readlane_b32 s0, v254, 63
	v_mov_b64_e32 v[4:5], s[24:25]
	v_readlane_b32 s1, v253, 0
	s_nop 1
	v_cmp_ge_i64_e32 vcc, s[0:1], v[4:5]
	s_cbranch_vccnz .LBB0_1287
	s_and_saveexec_b64 s[26:27], s[12:13]
	s_cbranch_execz .LBB0_1269
	v_readlane_b32 s0, v254, 62
	s_or_b32 s0, s41, s0
	v_readlane_b32 s1, v254, 61
	s_mul_i32 s0, s0, s1
	v_readlane_b32 s1, v254, 60
	s_add_i32 s0, s0, s1
	s_ashr_i32 s1, s0, 31
	s_lshr_b32 s1, s1, 26
	s_add_i32 s1, s0, s1
	s_ashr_i32 s28, s1, 6
	s_lshl_b32 s28, s28, 3
	s_sub_i32 s29, s41, s28
	s_min_i32 s29, s29, 8
	s_abs_i32 s29, s29
	v_cvt_f32_u32_e32 v4, s29
	s_sub_i32 s30, 0, s29
	s_andn2_b32 s1, s1, 63
	s_sub_i32 s0, s0, s1
	v_rcp_iflag_f32_e32 v4, v4
	s_ashr_i32 s1, s0, 31
	s_abs_i32 s0, s0
	v_mul_f32_e32 v4, 0x4f7ffffe, v4
	v_cvt_u32_f32_e32 v4, v4
	s_nop 0
	v_readfirstlane_b32 s31, v4
	s_mul_i32 s30, s30, s31
	s_mul_hi_u32 s30, s31, s30
	s_add_i32 s31, s31, s30
	s_mul_hi_u32 s30, s0, s31
	s_mul_i32 s30, s30, s29
	s_sub_i32 s0, s0, s30
	s_sub_i32 s30, s0, s29
	s_cmp_ge_u32 s0, s29
	s_cselect_b32 s0, s30, s0
	s_sub_i32 s30, s0, s29
	s_cmp_ge_u32 s0, s29
	s_cselect_b32 s0, s30, s0
	s_xor_b32 s0, s0, s1
	s_sub_i32 s0, s0, s1
	s_add_i32 s1, s28, s10
	s_add_i32 s1, s1, s0
	v_lshl_add_u32 v4, s1, 8, v2
	v_ashrrev_i32_e32 v5, 31, v4
	v_lshl_add_u64 v[4:5], v[4:5], 2, s[18:19]
	global_load_dword v43, v[4:5], off
.LBB0_1269:
	s_or_b64 exec, exec, s[26:27]
	v_readlane_b32 s0, v253, 4
	v_mov_b64_e32 v[4:5], s[24:25]
	v_readlane_b32 s1, v253, 5
	s_nop 1
	v_cmp_ge_i64_e32 vcc, s[0:1], v[4:5]
	s_cbranch_vccnz .LBB0_1287
	s_and_saveexec_b64 s[26:27], s[12:13]
	s_cbranch_execz .LBB0_1272
	v_readlane_b32 s0, v253, 3
	s_or_b32 s0, s41, s0
	v_readlane_b32 s1, v253, 2
	s_mul_i32 s0, s0, s1
	v_readlane_b32 s1, v253, 1
	s_add_i32 s0, s0, s1
	s_ashr_i32 s1, s0, 31
	s_lshr_b32 s1, s1, 26
	s_add_i32 s1, s0, s1
	s_ashr_i32 s28, s1, 6
	s_lshl_b32 s28, s28, 3
	s_sub_i32 s29, s41, s28
	s_min_i32 s29, s29, 8
	s_abs_i32 s29, s29
	v_cvt_f32_u32_e32 v4, s29
	s_sub_i32 s30, 0, s29
	s_andn2_b32 s1, s1, 63
	s_sub_i32 s0, s0, s1
	v_rcp_iflag_f32_e32 v4, v4
	s_ashr_i32 s1, s0, 31
	s_abs_i32 s0, s0
	v_mul_f32_e32 v4, 0x4f7ffffe, v4
	v_cvt_u32_f32_e32 v4, v4
	s_nop 0
	v_readfirstlane_b32 s31, v4
	s_mul_i32 s30, s30, s31
	s_mul_hi_u32 s30, s31, s30
	s_add_i32 s31, s31, s30
	s_mul_hi_u32 s30, s0, s31
	s_mul_i32 s30, s30, s29
	s_sub_i32 s0, s0, s30
	s_sub_i32 s30, s0, s29
	s_cmp_ge_u32 s0, s29
	s_cselect_b32 s0, s30, s0
	s_sub_i32 s30, s0, s29
	s_cmp_ge_u32 s0, s29
	s_cselect_b32 s0, s30, s0
	s_xor_b32 s0, s0, s1
	s_sub_i32 s0, s0, s1
	s_add_i32 s1, s28, s10
	s_add_i32 s1, s1, s0
	v_lshl_add_u32 v4, s1, 8, v2
	v_ashrrev_i32_e32 v5, 31, v4
	v_lshl_add_u64 v[4:5], v[4:5], 2, s[18:19]
	global_load_dword v44, v[4:5], off
.LBB0_1272:
	s_or_b64 exec, exec, s[26:27]
	v_readlane_b32 s0, v253, 9
	v_mov_b64_e32 v[4:5], s[24:25]
	v_readlane_b32 s1, v253, 10
	s_nop 1
	v_cmp_ge_i64_e32 vcc, s[0:1], v[4:5]
	s_cbranch_vccnz .LBB0_1287
	s_and_saveexec_b64 s[26:27], s[12:13]
	s_cbranch_execz .LBB0_1275
	v_readlane_b32 s0, v253, 8
	s_or_b32 s0, s41, s0
	v_readlane_b32 s1, v253, 7
	s_mul_i32 s0, s0, s1
	v_readlane_b32 s1, v253, 6
	s_add_i32 s0, s0, s1
	s_ashr_i32 s1, s0, 31
	s_lshr_b32 s1, s1, 26
	s_add_i32 s1, s0, s1
	s_ashr_i32 s28, s1, 6
	s_lshl_b32 s28, s28, 3
	s_sub_i32 s29, s41, s28
	s_min_i32 s29, s29, 8
	s_abs_i32 s29, s29
	v_cvt_f32_u32_e32 v4, s29
	s_sub_i32 s30, 0, s29
	s_andn2_b32 s1, s1, 63
	s_sub_i32 s0, s0, s1
	v_rcp_iflag_f32_e32 v4, v4
	s_ashr_i32 s1, s0, 31
	s_abs_i32 s0, s0
	v_mul_f32_e32 v4, 0x4f7ffffe, v4
	v_cvt_u32_f32_e32 v4, v4
	s_nop 0
	v_readfirstlane_b32 s31, v4
	s_mul_i32 s30, s30, s31
	s_mul_hi_u32 s30, s31, s30
	s_add_i32 s31, s31, s30
	s_mul_hi_u32 s30, s0, s31
	s_mul_i32 s30, s30, s29
	s_sub_i32 s0, s0, s30
	s_sub_i32 s30, s0, s29
	s_cmp_ge_u32 s0, s29
	s_cselect_b32 s0, s30, s0
	s_sub_i32 s30, s0, s29
	s_cmp_ge_u32 s0, s29
	s_cselect_b32 s0, s30, s0
	s_xor_b32 s0, s0, s1
	s_sub_i32 s0, s0, s1
	s_add_i32 s1, s28, s10
	s_add_i32 s1, s1, s0
	v_lshl_add_u32 v4, s1, 8, v2
	v_ashrrev_i32_e32 v5, 31, v4
	v_lshl_add_u64 v[4:5], v[4:5], 2, s[18:19]
	global_load_dword v45, v[4:5], off
.LBB0_1275:
	s_or_b64 exec, exec, s[26:27]
	v_readlane_b32 s0, v253, 14
	v_mov_b64_e32 v[4:5], s[24:25]
	v_readlane_b32 s1, v253, 15
	s_nop 1
	v_cmp_ge_i64_e32 vcc, s[0:1], v[4:5]
	s_cbranch_vccnz .LBB0_1287
	s_and_saveexec_b64 s[26:27], s[12:13]
	s_cbranch_execz .LBB0_1278
	v_readlane_b32 s0, v253, 13
	s_or_b32 s0, s41, s0
	v_readlane_b32 s1, v253, 12
	s_mul_i32 s0, s0, s1
	v_readlane_b32 s1, v253, 11
	s_add_i32 s0, s0, s1
	s_ashr_i32 s1, s0, 31
	s_lshr_b32 s1, s1, 26
	s_add_i32 s1, s0, s1
	s_ashr_i32 s28, s1, 6
	s_lshl_b32 s28, s28, 3
	s_sub_i32 s29, s41, s28
	s_min_i32 s29, s29, 8
	s_abs_i32 s29, s29
	v_cvt_f32_u32_e32 v4, s29
	s_sub_i32 s30, 0, s29
	s_andn2_b32 s1, s1, 63
	s_sub_i32 s0, s0, s1
	v_rcp_iflag_f32_e32 v4, v4
	s_ashr_i32 s1, s0, 31
	s_abs_i32 s0, s0
	v_mul_f32_e32 v4, 0x4f7ffffe, v4
	v_cvt_u32_f32_e32 v4, v4
	s_nop 0
	v_readfirstlane_b32 s31, v4
	s_mul_i32 s30, s30, s31
	s_mul_hi_u32 s30, s31, s30
	s_add_i32 s31, s31, s30
	s_mul_hi_u32 s30, s0, s31
	s_mul_i32 s30, s30, s29
	s_sub_i32 s0, s0, s30
	s_sub_i32 s30, s0, s29
	s_cmp_ge_u32 s0, s29
	s_cselect_b32 s0, s30, s0
	s_sub_i32 s30, s0, s29
	s_cmp_ge_u32 s0, s29
	s_cselect_b32 s0, s30, s0
	s_xor_b32 s0, s0, s1
	s_sub_i32 s0, s0, s1
	s_add_i32 s1, s28, s10
	s_add_i32 s1, s1, s0
	v_lshl_add_u32 v4, s1, 8, v2
	v_ashrrev_i32_e32 v5, 31, v4
	v_lshl_add_u64 v[4:5], v[4:5], 2, s[18:19]
	global_load_dword v46, v[4:5], off
.LBB0_1278:
	s_or_b64 exec, exec, s[26:27]
	v_readlane_b32 s0, v253, 19
	v_mov_b64_e32 v[4:5], s[24:25]
	v_readlane_b32 s1, v253, 20
	s_nop 1
	v_cmp_ge_i64_e32 vcc, s[0:1], v[4:5]
	s_cbranch_vccnz .LBB0_1287
	s_and_saveexec_b64 s[26:27], s[12:13]
	s_cbranch_execz .LBB0_1281
	v_readlane_b32 s0, v253, 18
	s_or_b32 s0, s41, s0
	v_readlane_b32 s1, v253, 17
	s_mul_i32 s0, s0, s1
	v_readlane_b32 s1, v253, 16
	s_add_i32 s0, s0, s1
	s_ashr_i32 s1, s0, 31
	s_lshr_b32 s1, s1, 26
	s_add_i32 s1, s0, s1
	s_ashr_i32 s28, s1, 6
	s_lshl_b32 s28, s28, 3
	s_sub_i32 s29, s41, s28
	s_min_i32 s29, s29, 8
	s_abs_i32 s29, s29
	v_cvt_f32_u32_e32 v4, s29
	s_sub_i32 s30, 0, s29
	s_andn2_b32 s1, s1, 63
	s_sub_i32 s0, s0, s1
	v_rcp_iflag_f32_e32 v4, v4
	s_ashr_i32 s1, s0, 31
	s_abs_i32 s0, s0
	v_mul_f32_e32 v4, 0x4f7ffffe, v4
	v_cvt_u32_f32_e32 v4, v4
	s_nop 0
	v_readfirstlane_b32 s31, v4
	s_mul_i32 s30, s30, s31
	s_mul_hi_u32 s30, s31, s30
	s_add_i32 s31, s31, s30
	s_mul_hi_u32 s30, s0, s31
	s_mul_i32 s30, s30, s29
	s_sub_i32 s0, s0, s30
	s_sub_i32 s30, s0, s29
	s_cmp_ge_u32 s0, s29
	s_cselect_b32 s0, s30, s0
	s_sub_i32 s30, s0, s29
	s_cmp_ge_u32 s0, s29
	s_cselect_b32 s0, s30, s0
	s_xor_b32 s0, s0, s1
	s_sub_i32 s0, s0, s1
	s_add_i32 s1, s28, s10
	s_add_i32 s1, s1, s0
	v_lshl_add_u32 v4, s1, 8, v2
	v_ashrrev_i32_e32 v5, 31, v4
	v_lshl_add_u64 v[4:5], v[4:5], 2, s[18:19]
	global_load_dword v47, v[4:5], off
.LBB0_1281:
	s_or_b64 exec, exec, s[26:27]
	v_readlane_b32 s0, v253, 24
	v_mov_b64_e32 v[4:5], s[24:25]
	v_readlane_b32 s1, v253, 25
	s_nop 1
	v_cmp_ge_i64_e32 vcc, s[0:1], v[4:5]
	s_cbranch_vccnz .LBB0_1287
	s_and_saveexec_b64 s[26:27], s[12:13]
	s_cbranch_execz .LBB0_1284
	v_readlane_b32 s0, v253, 23
	s_or_b32 s0, s41, s0
	v_readlane_b32 s1, v253, 22
	s_mul_i32 s0, s0, s1
	v_readlane_b32 s1, v253, 21
	s_add_i32 s0, s0, s1
	s_ashr_i32 s1, s0, 31
	s_lshr_b32 s1, s1, 26
	s_add_i32 s1, s0, s1
	s_ashr_i32 s12, s1, 6
	s_lshl_b32 s12, s12, 3
	s_sub_i32 s13, s41, s12
	s_min_i32 s13, s13, 8
	s_abs_i32 s13, s13
	v_cvt_f32_u32_e32 v4, s13
	s_sub_i32 s28, 0, s13
	s_andn2_b32 s1, s1, 63
	s_sub_i32 s0, s0, s1
	v_rcp_iflag_f32_e32 v4, v4
	s_ashr_i32 s1, s0, 31
	s_abs_i32 s0, s0
	v_mul_f32_e32 v4, 0x4f7ffffe, v4
	v_cvt_u32_f32_e32 v4, v4
	s_nop 0
	v_readfirstlane_b32 s29, v4
	s_mul_i32 s28, s28, s29
	s_mul_hi_u32 s28, s29, s28
	s_add_i32 s29, s29, s28
	s_mul_hi_u32 s28, s0, s29
	s_mul_i32 s28, s28, s13
	s_sub_i32 s0, s0, s28
	s_sub_i32 s28, s0, s13
	s_cmp_ge_u32 s0, s13
	s_cselect_b32 s0, s28, s0
	s_sub_i32 s28, s0, s13
	s_cmp_ge_u32 s0, s13
	s_cselect_b32 s0, s28, s0
	s_xor_b32 s0, s0, s1
	s_sub_i32 s0, s0, s1
	s_add_i32 s1, s12, s10
	s_add_i32 s1, s1, s0
	v_lshl_add_u32 v4, s1, 8, v2
	v_ashrrev_i32_e32 v5, 31, v4
	v_lshl_add_u64 v[4:5], v[4:5], 2, s[18:19]
	global_load_dword v48, v[4:5], off
.LBB0_1284:
	s_or_b64 exec, exec, s[26:27]
	v_readlane_b32 s0, v253, 27
	v_mov_b64_e32 v[4:5], s[24:25]
	v_readlane_b32 s1, v253, 28
	s_nop 1
	v_cmp_lt_i64_e32 vcc, s[0:1], v[4:5]
	s_xor_b64 s[0:1], s[8:9], -1
	s_and_b64 s[0:1], vcc, s[0:1]
	s_and_saveexec_b64 s[8:9], s[0:1]
	s_cbranch_execz .LBB0_1286
	v_readlane_b32 s0, v253, 30
	s_or_b32 s0, s41, s0
	v_readlane_b32 s1, v253, 29
	s_mul_i32 s0, s0, s1
	v_readlane_b32 s1, v253, 26
	s_add_i32 s0, s0, s1
	s_ashr_i32 s1, s0, 31
	s_lshr_b32 s1, s1, 26
	s_add_i32 s1, s0, s1
	s_ashr_i32 s12, s1, 6
	s_lshl_b32 s12, s12, 3
	s_sub_i32 s13, s41, s12
	s_min_i32 s13, s13, 8
	s_abs_i32 s13, s13
	v_cvt_f32_u32_e32 v4, s13
	s_sub_i32 s26, 0, s13
	s_andn2_b32 s1, s1, 63
	s_sub_i32 s0, s0, s1
	v_rcp_iflag_f32_e32 v4, v4
	s_ashr_i32 s1, s0, 31
	s_abs_i32 s0, s0
	v_mul_f32_e32 v4, 0x4f7ffffe, v4
	v_cvt_u32_f32_e32 v4, v4
	s_nop 0
	v_readfirstlane_b32 s27, v4
	s_mul_i32 s26, s26, s27
	s_mul_hi_u32 s26, s27, s26
	s_add_i32 s27, s27, s26
	s_mul_hi_u32 s26, s0, s27
	s_mul_i32 s26, s26, s13
	s_sub_i32 s0, s0, s26
	s_sub_i32 s26, s0, s13
	s_cmp_ge_u32 s0, s13
	s_cselect_b32 s0, s26, s0
	s_sub_i32 s26, s0, s13
	s_cmp_ge_u32 s0, s13
	s_cselect_b32 s0, s26, s0
	s_xor_b32 s0, s0, s1
	s_sub_i32 s0, s0, s1
	s_add_i32 s1, s12, s10
	s_add_i32 s1, s1, s0
	v_lshl_add_u32 v4, s1, 8, v2
	v_ashrrev_i32_e32 v5, 31, v4
	v_lshl_add_u64 v[4:5], v[4:5], 2, s[18:19]
	global_load_dword v49, v[4:5], off

.LBB0_1978:
	s_sub_i32 s0, 0x200, s8
	s_min_i32 s11, s0, s90
	s_lshl_b32 s26, s11, 3
	s_ashr_i32 s27, s26, 31
	v_mov_b32_e32 v2, v0
	s_cmp_lt_i32 s2, s26
	s_cselect_b64 s[16:17], -1, 0
	s_cmp_ge_i32 s2, s26
	v_readfirstlane_b32 s42, v2
	s_cbranch_scc1 .Lgidx_skip_2
	s_movk_i32 s0, 0xff
	v_cmp_lt_i32_e64 s[12:13], s0, v2
	s_movk_i32 s0, 0x100
	v_lshl_add_u32 v3, v2, 2, s95
	v_cmp_gt_i32_e64 s[14:15], s0, v2
	s_and_saveexec_b64 s[28:29], s[14:15]
	s_cbranch_execz .LBB0_1981
	s_or_b32 s0, s11, s80
	s_mul_i32 s0, s0, s76
	s_add_i32 s0, s0, s91
	s_ashr_i32 s1, s0, 31
	s_lshr_b32 s1, s1, 26
	s_add_i32 s1, s0, s1
	s_ashr_i32 s30, s1, 6
	s_lshl_b32 s30, s30, 3
	s_sub_i32 s31, s11, s30
	s_min_i32 s31, s31, 8
	s_abs_i32 s31, s31
	v_cvt_f32_u32_e32 v4, s31
	s_sub_i32 s34, 0, s31
	s_andn2_b32 s1, s1, 63
	s_sub_i32 s0, s0, s1
	v_rcp_iflag_f32_e32 v4, v4
	s_ashr_i32 s1, s0, 31
	s_abs_i32 s0, s0
	v_mul_f32_e32 v4, 0x4f7ffffe, v4
	v_cvt_u32_f32_e32 v4, v4
	s_nop 0
	v_readfirstlane_b32 s35, v4
	s_mul_i32 s34, s34, s35
	s_mul_hi_u32 s34, s35, s34
	s_add_i32 s35, s35, s34
	s_mul_hi_u32 s34, s0, s35
	s_mul_i32 s34, s34, s31
	s_sub_i32 s0, s0, s34
	s_sub_i32 s34, s0, s31
	s_cmp_ge_u32 s0, s31
	s_cselect_b32 s0, s34, s0
	s_sub_i32 s34, s0, s31
	s_cmp_ge_u32 s0, s31
	s_cselect_b32 s0, s34, s0
	s_xor_b32 s0, s0, s1
	s_sub_i32 s0, s0, s1
	s_add_i32 s1, s30, s8
	s_add_i32 s1, s1, s0
	v_lshl_add_u32 v4, s1, 8, v2
	v_ashrrev_i32_e32 v5, 31, v4
	v_lshl_add_u64 v[4:5], v[4:5], 2, s[20:21]
	global_load_dword v34, v[4:5], off
.LBB0_1981:
	s_or_b64 exec, exec, s[28:29]
	v_readlane_b32 s0, v254, 23
	v_mov_b64_e32 v[4:5], s[26:27]
	v_readlane_b32 s1, v254, 24
	s_nop 1
	v_cmp_ge_i64_e32 vcc, s[0:1], v[4:5]
	s_cbranch_vccnz .LBB0_2026
	s_and_saveexec_b64 s[28:29], s[14:15]
	s_cbranch_execz .LBB0_1984
	v_readlane_b32 s0, v254, 22
	s_or_b32 s0, s11, s0
	v_readlane_b32 s1, v254, 21
	s_mul_i32 s0, s0, s1
	s_add_i32 s0, s0, s89
	s_ashr_i32 s1, s0, 31
	s_lshr_b32 s1, s1, 26
	s_add_i32 s1, s0, s1
	s_ashr_i32 s30, s1, 6
	s_lshl_b32 s30, s30, 3
	s_sub_i32 s31, s11, s30
	s_min_i32 s31, s31, 8
	s_abs_i32 s31, s31
	v_cvt_f32_u32_e32 v4, s31
	s_sub_i32 s34, 0, s31
	s_andn2_b32 s1, s1, 63
	s_sub_i32 s0, s0, s1
	v_rcp_iflag_f32_e32 v4, v4
	s_ashr_i32 s1, s0, 31
	s_abs_i32 s0, s0
	v_mul_f32_e32 v4, 0x4f7ffffe, v4
	v_cvt_u32_f32_e32 v4, v4
	s_nop 0
	v_readfirstlane_b32 s35, v4
	s_mul_i32 s34, s34, s35
	s_mul_hi_u32 s34, s35, s34
	s_add_i32 s35, s35, s34
	s_mul_hi_u32 s34, s0, s35
	s_mul_i32 s34, s34, s31
	s_sub_i32 s0, s0, s34
	s_sub_i32 s34, s0, s31
	s_cmp_ge_u32 s0, s31
	s_cselect_b32 s0, s34, s0
	s_sub_i32 s34, s0, s31
	s_cmp_ge_u32 s0, s31
	s_cselect_b32 s0, s34, s0
	s_xor_b32 s0, s0, s1
	s_sub_i32 s0, s0, s1
	s_add_i32 s1, s30, s8
	s_add_i32 s1, s1, s0
	v_lshl_add_u32 v4, s1, 8, v2
	v_ashrrev_i32_e32 v5, 31, v4
	v_lshl_add_u64 v[4:5], v[4:5], 2, s[20:21]
	global_load_dword v35, v[4:5], off
.LBB0_1984:
	s_or_b64 exec, exec, s[28:29]
	v_readlane_b32 s0, v254, 28
	v_mov_b64_e32 v[4:5], s[26:27]
	v_readlane_b32 s1, v254, 29
	s_nop 1
	v_cmp_ge_i64_e32 vcc, s[0:1], v[4:5]
	s_cbranch_vccnz .LBB0_2026
	s_and_saveexec_b64 s[28:29], s[14:15]
	s_cbranch_execz .LBB0_1987
	v_readlane_b32 s0, v254, 27
	s_or_b32 s0, s11, s0
	v_readlane_b32 s1, v254, 26
	s_mul_i32 s0, s0, s1
	v_readlane_b32 s1, v254, 25
	s_add_i32 s0, s0, s1
	s_ashr_i32 s1, s0, 31
	s_lshr_b32 s1, s1, 26
	s_add_i32 s1, s0, s1
	s_ashr_i32 s30, s1, 6
	s_lshl_b32 s30, s30, 3
	s_sub_i32 s31, s11, s30
	s_min_i32 s31, s31, 8
	s_abs_i32 s31, s31
	v_cvt_f32_u32_e32 v4, s31
	s_sub_i32 s34, 0, s31
	s_andn2_b32 s1, s1, 63
	s_sub_i32 s0, s0, s1
	v_rcp_iflag_f32_e32 v4, v4
	s_ashr_i32 s1, s0, 31
	s_abs_i32 s0, s0
	v_mul_f32_e32 v4, 0x4f7ffffe, v4
	v_cvt_u32_f32_e32 v4, v4
	s_nop 0
	v_readfirstlane_b32 s35, v4
	s_mul_i32 s34, s34, s35
	s_mul_hi_u32 s34, s35, s34
	s_add_i32 s35, s35, s34
	s_mul_hi_u32 s34, s0, s35
	s_mul_i32 s34, s34, s31
	s_sub_i32 s0, s0, s34
	s_sub_i32 s34, s0, s31
	s_cmp_ge_u32 s0, s31
	s_cselect_b32 s0, s34, s0
	s_sub_i32 s34, s0, s31
	s_cmp_ge_u32 s0, s31
	s_cselect_b32 s0, s34, s0
	s_xor_b32 s0, s0, s1
	s_sub_i32 s0, s0, s1
	s_add_i32 s1, s30, s8
	s_add_i32 s1, s1, s0
	v_lshl_add_u32 v4, s1, 8, v2
	v_ashrrev_i32_e32 v5, 31, v4
	v_lshl_add_u64 v[4:5], v[4:5], 2, s[20:21]
	global_load_dword v36, v[4:5], off
.LBB0_1987:
	s_or_b64 exec, exec, s[28:29]
	v_readlane_b32 s0, v254, 33
	v_mov_b64_e32 v[4:5], s[26:27]
	v_readlane_b32 s1, v254, 34
	s_nop 1
	v_cmp_ge_i64_e32 vcc, s[0:1], v[4:5]
	s_cbranch_vccnz .LBB0_2026
	s_and_saveexec_b64 s[28:29], s[14:15]
	s_cbranch_execz .LBB0_1990
	v_readlane_b32 s0, v254, 32
	s_or_b32 s0, s11, s0
	v_readlane_b32 s1, v254, 31
	s_mul_i32 s0, s0, s1
	v_readlane_b32 s1, v254, 30
	s_add_i32 s0, s0, s1
	s_ashr_i32 s1, s0, 31
	s_lshr_b32 s1, s1, 26
	s_add_i32 s1, s0, s1
	s_ashr_i32 s30, s1, 6
	s_lshl_b32 s30, s30, 3
	s_sub_i32 s31, s11, s30
	s_min_i32 s31, s31, 8
	s_abs_i32 s31, s31
	v_cvt_f32_u32_e32 v4, s31
	s_sub_i32 s34, 0, s31
	s_andn2_b32 s1, s1, 63
	s_sub_i32 s0, s0, s1
	v_rcp_iflag_f32_e32 v4, v4
	s_ashr_i32 s1, s0, 31
	s_abs_i32 s0, s0
	v_mul_f32_e32 v4, 0x4f7ffffe, v4
	v_cvt_u32_f32_e32 v4, v4
	s_nop 0
	v_readfirstlane_b32 s35, v4
	s_mul_i32 s34, s34, s35
	s_mul_hi_u32 s34, s35, s34
	s_add_i32 s35, s35, s34
	s_mul_hi_u32 s34, s0, s35
	s_mul_i32 s34, s34, s31
	s_sub_i32 s0, s0, s34
	s_sub_i32 s34, s0, s31
	s_cmp_ge_u32 s0, s31
	s_cselect_b32 s0, s34, s0
	s_sub_i32 s34, s0, s31
	s_cmp_ge_u32 s0, s31
	s_cselect_b32 s0, s34, s0
	s_xor_b32 s0, s0, s1
	s_sub_i32 s0, s0, s1
	s_add_i32 s1, s30, s8
	s_add_i32 s1, s1, s0
	v_lshl_add_u32 v4, s1, 8, v2
	v_ashrrev_i32_e32 v5, 31, v4
	v_lshl_add_u64 v[4:5], v[4:5], 2, s[20:21]
	global_load_dword v37, v[4:5], off
.LBB0_1990:
	s_or_b64 exec, exec, s[28:29]
	v_readlane_b32 s0, v254, 38
	v_mov_b64_e32 v[4:5], s[26:27]
	v_readlane_b32 s1, v254, 39
	s_nop 1
	v_cmp_ge_i64_e32 vcc, s[0:1], v[4:5]
	s_cbranch_vccnz .LBB0_2026
	s_and_saveexec_b64 s[28:29], s[14:15]
	s_cbranch_execz .LBB0_1993
	v_readlane_b32 s0, v254, 37
	s_or_b32 s0, s11, s0
	v_readlane_b32 s1, v254, 36
	s_mul_i32 s0, s0, s1
	v_readlane_b32 s1, v254, 35
	s_add_i32 s0, s0, s1
	s_ashr_i32 s1, s0, 31
	s_lshr_b32 s1, s1, 26
	s_add_i32 s1, s0, s1
	s_ashr_i32 s30, s1, 6
	s_lshl_b32 s30, s30, 3
	s_sub_i32 s31, s11, s30
	s_min_i32 s31, s31, 8
	s_abs_i32 s31, s31
	v_cvt_f32_u32_e32 v4, s31
	s_sub_i32 s34, 0, s31
	s_andn2_b32 s1, s1, 63
	s_sub_i32 s0, s0, s1
	v_rcp_iflag_f32_e32 v4, v4
	s_ashr_i32 s1, s0, 31
	s_abs_i32 s0, s0
	v_mul_f32_e32 v4, 0x4f7ffffe, v4
	v_cvt_u32_f32_e32 v4, v4
	s_nop 0
	v_readfirstlane_b32 s35, v4
	s_mul_i32 s34, s34, s35
	s_mul_hi_u32 s34, s35, s34
	s_add_i32 s35, s35, s34
	s_mul_hi_u32 s34, s0, s35
	s_mul_i32 s34, s34, s31
	s_sub_i32 s0, s0, s34
	s_sub_i32 s34, s0, s31
	s_cmp_ge_u32 s0, s31
	s_cselect_b32 s0, s34, s0
	s_sub_i32 s34, s0, s31
	s_cmp_ge_u32 s0, s31
	s_cselect_b32 s0, s34, s0
	s_xor_b32 s0, s0, s1
	s_sub_i32 s0, s0, s1
	s_add_i32 s1, s30, s8
	s_add_i32 s1, s1, s0
	v_lshl_add_u32 v4, s1, 8, v2
	v_ashrrev_i32_e32 v5, 31, v4
	v_lshl_add_u64 v[4:5], v[4:5], 2, s[20:21]
	global_load_dword v38, v[4:5], off
.LBB0_1993:
	s_or_b64 exec, exec, s[28:29]
	v_readlane_b32 s0, v254, 43
	v_mov_b64_e32 v[4:5], s[26:27]
	v_readlane_b32 s1, v254, 44
	s_nop 1
	v_cmp_ge_i64_e32 vcc, s[0:1], v[4:5]
	s_cbranch_vccnz .LBB0_2026
	s_and_saveexec_b64 s[28:29], s[14:15]
	s_cbranch_execz .LBB0_1996
	v_readlane_b32 s0, v254, 42
	s_or_b32 s0, s11, s0
	v_readlane_b32 s1, v254, 41
	s_mul_i32 s0, s0, s1
	v_readlane_b32 s1, v254, 40
	s_add_i32 s0, s0, s1
	s_ashr_i32 s1, s0, 31
	s_lshr_b32 s1, s1, 26
	s_add_i32 s1, s0, s1
	s_ashr_i32 s30, s1, 6
	s_lshl_b32 s30, s30, 3
	s_sub_i32 s31, s11, s30
	s_min_i32 s31, s31, 8
	s_abs_i32 s31, s31
	v_cvt_f32_u32_e32 v4, s31
	s_sub_i32 s34, 0, s31
	s_andn2_b32 s1, s1, 63
	s_sub_i32 s0, s0, s1
	v_rcp_iflag_f32_e32 v4, v4
	s_ashr_i32 s1, s0, 31
	s_abs_i32 s0, s0
	v_mul_f32_e32 v4, 0x4f7ffffe, v4
	v_cvt_u32_f32_e32 v4, v4
	s_nop 0
	v_readfirstlane_b32 s35, v4
	s_mul_i32 s34, s34, s35
	s_mul_hi_u32 s34, s35, s34
	s_add_i32 s35, s35, s34
	s_mul_hi_u32 s34, s0, s35
	s_mul_i32 s34, s34, s31
	s_sub_i32 s0, s0, s34
	s_sub_i32 s34, s0, s31
	s_cmp_ge_u32 s0, s31
	s_cselect_b32 s0, s34, s0
	s_sub_i32 s34, s0, s31
	s_cmp_ge_u32 s0, s31
	s_cselect_b32 s0, s34, s0
	s_xor_b32 s0, s0, s1
	s_sub_i32 s0, s0, s1
	s_add_i32 s1, s30, s8
	s_add_i32 s1, s1, s0
	v_lshl_add_u32 v4, s1, 8, v2
	v_ashrrev_i32_e32 v5, 31, v4
	v_lshl_add_u64 v[4:5], v[4:5], 2, s[20:21]
	global_load_dword v39, v[4:5], off
.LBB0_1996:
	s_or_b64 exec, exec, s[28:29]
	v_readlane_b32 s0, v254, 48
	v_mov_b64_e32 v[4:5], s[26:27]
	v_readlane_b32 s1, v254, 49
	s_nop 1
	v_cmp_ge_i64_e32 vcc, s[0:1], v[4:5]
	s_cbranch_vccnz .LBB0_2026
	s_and_saveexec_b64 s[28:29], s[14:15]
	s_cbranch_execz .LBB0_1999
	v_readlane_b32 s0, v254, 47
	s_or_b32 s0, s11, s0
	v_readlane_b32 s1, v254, 46
	s_mul_i32 s0, s0, s1
	v_readlane_b32 s1, v254, 45
	s_add_i32 s0, s0, s1
	s_ashr_i32 s1, s0, 31
	s_lshr_b32 s1, s1, 26
	s_add_i32 s1, s0, s1
	s_ashr_i32 s30, s1, 6
	s_lshl_b32 s30, s30, 3
	s_sub_i32 s31, s11, s30
	s_min_i32 s31, s31, 8
	s_abs_i32 s31, s31
	v_cvt_f32_u32_e32 v4, s31
	s_sub_i32 s34, 0, s31
	s_andn2_b32 s1, s1, 63
	s_sub_i32 s0, s0, s1
	v_rcp_iflag_f32_e32 v4, v4
	s_ashr_i32 s1, s0, 31
	s_abs_i32 s0, s0
	v_mul_f32_e32 v4, 0x4f7ffffe, v4
	v_cvt_u32_f32_e32 v4, v4
	s_nop 0
	v_readfirstlane_b32 s35, v4
	s_mul_i32 s34, s34, s35
	s_mul_hi_u32 s34, s35, s34
	s_add_i32 s35, s35, s34
	s_mul_hi_u32 s34, s0, s35
	s_mul_i32 s34, s34, s31
	s_sub_i32 s0, s0, s34
	s_sub_i32 s34, s0, s31
	s_cmp_ge_u32 s0, s31
	s_cselect_b32 s0, s34, s0
	s_sub_i32 s34, s0, s31
	s_cmp_ge_u32 s0, s31
	s_cselect_b32 s0, s34, s0
	s_xor_b32 s0, s0, s1
	s_sub_i32 s0, s0, s1
	s_add_i32 s1, s30, s8
	s_add_i32 s1, s1, s0
	v_lshl_add_u32 v4, s1, 8, v2
	v_ashrrev_i32_e32 v5, 31, v4
	v_lshl_add_u64 v[4:5], v[4:5], 2, s[20:21]
	global_load_dword v40, v[4:5], off
.LBB0_1999:
	s_or_b64 exec, exec, s[28:29]
	v_readlane_b32 s0, v254, 53
	v_mov_b64_e32 v[4:5], s[26:27]
	v_readlane_b32 s1, v254, 54
	s_nop 1
	v_cmp_ge_i64_e32 vcc, s[0:1], v[4:5]
	s_cbranch_vccnz .LBB0_2026
	s_and_saveexec_b64 s[28:29], s[14:15]
	s_cbranch_execz .LBB0_2002
	v_readlane_b32 s0, v254, 52
	s_or_b32 s0, s11, s0
	v_readlane_b32 s1, v254, 51
	s_mul_i32 s0, s0, s1
	v_readlane_b32 s1, v254, 50
	s_add_i32 s0, s0, s1
	s_ashr_i32 s1, s0, 31
	s_lshr_b32 s1, s1, 26
	s_add_i32 s1, s0, s1
	s_ashr_i32 s30, s1, 6
	s_lshl_b32 s30, s30, 3
	s_sub_i32 s31, s11, s30
	s_min_i32 s31, s31, 8
	s_abs_i32 s31, s31
	v_cvt_f32_u32_e32 v4, s31
	s_sub_i32 s34, 0, s31
	s_andn2_b32 s1, s1, 63
	s_sub_i32 s0, s0, s1
	v_rcp_iflag_f32_e32 v4, v4
	s_ashr_i32 s1, s0, 31
	s_abs_i32 s0, s0
	v_mul_f32_e32 v4, 0x4f7ffffe, v4
	v_cvt_u32_f32_e32 v4, v4
	s_nop 0
	v_readfirstlane_b32 s35, v4
	s_mul_i32 s34, s34, s35
	s_mul_hi_u32 s34, s35, s34
	s_add_i32 s35, s35, s34
	s_mul_hi_u32 s34, s0, s35
	s_mul_i32 s34, s34, s31
	s_sub_i32 s0, s0, s34
	s_sub_i32 s34, s0, s31
	s_cmp_ge_u32 s0, s31
	s_cselect_b32 s0, s34, s0
	s_sub_i32 s34, s0, s31
	s_cmp_ge_u32 s0, s31
	s_cselect_b32 s0, s34, s0
	s_xor_b32 s0, s0, s1
	s_sub_i32 s0, s0, s1
	s_add_i32 s1, s30, s8
	s_add_i32 s1, s1, s0
	v_lshl_add_u32 v4, s1, 8, v2
	v_ashrrev_i32_e32 v5, 31, v4
	v_lshl_add_u64 v[4:5], v[4:5], 2, s[20:21]
	global_load_dword v41, v[4:5], off
.LBB0_2002:
	s_or_b64 exec, exec, s[28:29]
	v_readlane_b32 s0, v254, 58
	v_mov_b64_e32 v[4:5], s[26:27]
	v_readlane_b32 s1, v254, 59
	s_nop 1
	v_cmp_ge_i64_e32 vcc, s[0:1], v[4:5]
	s_cbranch_vccnz .LBB0_2026
	s_and_saveexec_b64 s[28:29], s[14:15]
	s_cbranch_execz .LBB0_2005
	v_readlane_b32 s0, v254, 57
	s_or_b32 s0, s11, s0
	v_readlane_b32 s1, v254, 56
	s_mul_i32 s0, s0, s1
	v_readlane_b32 s1, v254, 55
	s_add_i32 s0, s0, s1
	s_ashr_i32 s1, s0, 31
	s_lshr_b32 s1, s1, 26
	s_add_i32 s1, s0, s1
	s_ashr_i32 s30, s1, 6
	s_lshl_b32 s30, s30, 3
	s_sub_i32 s31, s11, s30
	s_min_i32 s31, s31, 8
	s_abs_i32 s31, s31
	v_cvt_f32_u32_e32 v4, s31
	s_sub_i32 s34, 0, s31
	s_andn2_b32 s1, s1, 63
	s_sub_i32 s0, s0, s1
	v_rcp_iflag_f32_e32 v4, v4
	s_ashr_i32 s1, s0, 31
	s_abs_i32 s0, s0
	v_mul_f32_e32 v4, 0x4f7ffffe, v4
	v_cvt_u32_f32_e32 v4, v4
	s_nop 0
	v_readfirstlane_b32 s35, v4
	s_mul_i32 s34, s34, s35
	s_mul_hi_u32 s34, s35, s34
	s_add_i32 s35, s35, s34
	s_mul_hi_u32 s34, s0, s35
	s_mul_i32 s34, s34, s31
	s_sub_i32 s0, s0, s34
	s_sub_i32 s34, s0, s31
	s_cmp_ge_u32 s0, s31
	s_cselect_b32 s0, s34, s0
	s_sub_i32 s34, s0, s31
	s_cmp_ge_u32 s0, s31
	s_cselect_b32 s0, s34, s0
	s_xor_b32 s0, s0, s1
	s_sub_i32 s0, s0, s1
	s_add_i32 s1, s30, s8
	s_add_i32 s1, s1, s0
	v_lshl_add_u32 v4, s1, 8, v2
	v_ashrrev_i32_e32 v5, 31, v4
	v_lshl_add_u64 v[4:5], v[4:5], 2, s[20:21]
	global_load_dword v42, v[4:5], off
.LBB0_2005:
	s_or_b64 exec, exec, s[28:29]
	v_readlane_b32 s0, v254, 63
	v_mov_b64_e32 v[4:5], s[26:27]
	v_readlane_b32 s1, v253, 0
	s_nop 1
	v_cmp_ge_i64_e32 vcc, s[0:1], v[4:5]
	s_cbranch_vccnz .LBB0_2026
	s_and_saveexec_b64 s[28:29], s[14:15]
	s_cbranch_execz .LBB0_2008
	v_readlane_b32 s0, v254, 62
	s_or_b32 s0, s11, s0
	v_readlane_b32 s1, v254, 61
	s_mul_i32 s0, s0, s1
	v_readlane_b32 s1, v254, 60
	s_add_i32 s0, s0, s1
	s_ashr_i32 s1, s0, 31
	s_lshr_b32 s1, s1, 26
	s_add_i32 s1, s0, s1
	s_ashr_i32 s30, s1, 6
	s_lshl_b32 s30, s30, 3
	s_sub_i32 s31, s11, s30
	s_min_i32 s31, s31, 8
	s_abs_i32 s31, s31
	v_cvt_f32_u32_e32 v4, s31
	s_sub_i32 s34, 0, s31
	s_andn2_b32 s1, s1, 63
	s_sub_i32 s0, s0, s1
	v_rcp_iflag_f32_e32 v4, v4
	s_ashr_i32 s1, s0, 31
	s_abs_i32 s0, s0
	v_mul_f32_e32 v4, 0x4f7ffffe, v4
	v_cvt_u32_f32_e32 v4, v4
	s_nop 0
	v_readfirstlane_b32 s35, v4
	s_mul_i32 s34, s34, s35
	s_mul_hi_u32 s34, s35, s34
	s_add_i32 s35, s35, s34
	s_mul_hi_u32 s34, s0, s35
	s_mul_i32 s34, s34, s31
	s_sub_i32 s0, s0, s34
	s_sub_i32 s34, s0, s31
	s_cmp_ge_u32 s0, s31
	s_cselect_b32 s0, s34, s0
	s_sub_i32 s34, s0, s31
	s_cmp_ge_u32 s0, s31
	s_cselect_b32 s0, s34, s0
	s_xor_b32 s0, s0, s1
	s_sub_i32 s0, s0, s1
	s_add_i32 s1, s30, s8
	s_add_i32 s1, s1, s0
	v_lshl_add_u32 v4, s1, 8, v2
	v_ashrrev_i32_e32 v5, 31, v4
	v_lshl_add_u64 v[4:5], v[4:5], 2, s[20:21]
	global_load_dword v43, v[4:5], off
.LBB0_2008:
	s_or_b64 exec, exec, s[28:29]
	v_readlane_b32 s0, v253, 4
	v_mov_b64_e32 v[4:5], s[26:27]
	v_readlane_b32 s1, v253, 5
	s_nop 1
	v_cmp_ge_i64_e32 vcc, s[0:1], v[4:5]
	s_cbranch_vccnz .LBB0_2026
	s_and_saveexec_b64 s[28:29], s[14:15]
	s_cbranch_execz .LBB0_2011
	v_readlane_b32 s0, v253, 3
	s_or_b32 s0, s11, s0
	v_readlane_b32 s1, v253, 2
	s_mul_i32 s0, s0, s1
	v_readlane_b32 s1, v253, 1
	s_add_i32 s0, s0, s1
	s_ashr_i32 s1, s0, 31
	s_lshr_b32 s1, s1, 26
	s_add_i32 s1, s0, s1
	s_ashr_i32 s30, s1, 6
	s_lshl_b32 s30, s30, 3
	s_sub_i32 s31, s11, s30
	s_min_i32 s31, s31, 8
	s_abs_i32 s31, s31
	v_cvt_f32_u32_e32 v4, s31
	s_sub_i32 s34, 0, s31
	s_andn2_b32 s1, s1, 63
	s_sub_i32 s0, s0, s1
	v_rcp_iflag_f32_e32 v4, v4
	s_ashr_i32 s1, s0, 31
	s_abs_i32 s0, s0
	v_mul_f32_e32 v4, 0x4f7ffffe, v4
	v_cvt_u32_f32_e32 v4, v4
	s_nop 0
	v_readfirstlane_b32 s35, v4
	s_mul_i32 s34, s34, s35
	s_mul_hi_u32 s34, s35, s34
	s_add_i32 s35, s35, s34
	s_mul_hi_u32 s34, s0, s35
	s_mul_i32 s34, s34, s31
	s_sub_i32 s0, s0, s34
	s_sub_i32 s34, s0, s31
	s_cmp_ge_u32 s0, s31
	s_cselect_b32 s0, s34, s0
	s_sub_i32 s34, s0, s31
	s_cmp_ge_u32 s0, s31
	s_cselect_b32 s0, s34, s0
	s_xor_b32 s0, s0, s1
	s_sub_i32 s0, s0, s1
	s_add_i32 s1, s30, s8
	s_add_i32 s1, s1, s0
	v_lshl_add_u32 v4, s1, 8, v2
	v_ashrrev_i32_e32 v5, 31, v4
	v_lshl_add_u64 v[4:5], v[4:5], 2, s[20:21]
	global_load_dword v44, v[4:5], off
.LBB0_2011:
	s_or_b64 exec, exec, s[28:29]
	v_readlane_b32 s0, v253, 9
	v_mov_b64_e32 v[4:5], s[26:27]
	v_readlane_b32 s1, v253, 10
	s_nop 1
	v_cmp_ge_i64_e32 vcc, s[0:1], v[4:5]
	s_cbranch_vccnz .LBB0_2026
	s_and_saveexec_b64 s[28:29], s[14:15]
	s_cbranch_execz .LBB0_2014
	v_readlane_b32 s0, v253, 8
	s_or_b32 s0, s11, s0
	v_readlane_b32 s1, v253, 7
	s_mul_i32 s0, s0, s1
	v_readlane_b32 s1, v253, 6
	s_add_i32 s0, s0, s1
	s_ashr_i32 s1, s0, 31
	s_lshr_b32 s1, s1, 26
	s_add_i32 s1, s0, s1
	s_ashr_i32 s30, s1, 6
	s_lshl_b32 s30, s30, 3
	s_sub_i32 s31, s11, s30
	s_min_i32 s31, s31, 8
	s_abs_i32 s31, s31
	v_cvt_f32_u32_e32 v4, s31
	s_sub_i32 s34, 0, s31
	s_andn2_b32 s1, s1, 63
	s_sub_i32 s0, s0, s1
	v_rcp_iflag_f32_e32 v4, v4
	s_ashr_i32 s1, s0, 31
	s_abs_i32 s0, s0
	v_mul_f32_e32 v4, 0x4f7ffffe, v4
	v_cvt_u32_f32_e32 v4, v4
	s_nop 0
	v_readfirstlane_b32 s35, v4
	s_mul_i32 s34, s34, s35
	s_mul_hi_u32 s34, s35, s34
	s_add_i32 s35, s35, s34
	s_mul_hi_u32 s34, s0, s35
	s_mul_i32 s34, s34, s31
	s_sub_i32 s0, s0, s34
	s_sub_i32 s34, s0, s31
	s_cmp_ge_u32 s0, s31
	s_cselect_b32 s0, s34, s0
	s_sub_i32 s34, s0, s31
	s_cmp_ge_u32 s0, s31
	s_cselect_b32 s0, s34, s0
	s_xor_b32 s0, s0, s1
	s_sub_i32 s0, s0, s1
	s_add_i32 s1, s30, s8
	s_add_i32 s1, s1, s0
	v_lshl_add_u32 v4, s1, 8, v2
	v_ashrrev_i32_e32 v5, 31, v4
	v_lshl_add_u64 v[4:5], v[4:5], 2, s[20:21]
	global_load_dword v45, v[4:5], off
.LBB0_2014:
	s_or_b64 exec, exec, s[28:29]
	v_readlane_b32 s0, v253, 14
	v_mov_b64_e32 v[4:5], s[26:27]
	v_readlane_b32 s1, v253, 15
	s_nop 1
	v_cmp_ge_i64_e32 vcc, s[0:1], v[4:5]
	s_cbranch_vccnz .LBB0_2026
	s_and_saveexec_b64 s[28:29], s[14:15]
	s_cbranch_execz .LBB0_2017
	v_readlane_b32 s0, v253, 13
	s_or_b32 s0, s11, s0
	v_readlane_b32 s1, v253, 12
	s_mul_i32 s0, s0, s1
	v_readlane_b32 s1, v253, 11
	s_add_i32 s0, s0, s1
	s_ashr_i32 s1, s0, 31
	s_lshr_b32 s1, s1, 26
	s_add_i32 s1, s0, s1
	s_ashr_i32 s30, s1, 6
	s_lshl_b32 s30, s30, 3
	s_sub_i32 s31, s11, s30
	s_min_i32 s31, s31, 8
	s_abs_i32 s31, s31
	v_cvt_f32_u32_e32 v4, s31
	s_sub_i32 s34, 0, s31
	s_andn2_b32 s1, s1, 63
	s_sub_i32 s0, s0, s1
	v_rcp_iflag_f32_e32 v4, v4
	s_ashr_i32 s1, s0, 31
	s_abs_i32 s0, s0
	v_mul_f32_e32 v4, 0x4f7ffffe, v4
	v_cvt_u32_f32_e32 v4, v4
	s_nop 0
	v_readfirstlane_b32 s35, v4
	s_mul_i32 s34, s34, s35
	s_mul_hi_u32 s34, s35, s34
	s_add_i32 s35, s35, s34
	s_mul_hi_u32 s34, s0, s35
	s_mul_i32 s34, s34, s31
	s_sub_i32 s0, s0, s34
	s_sub_i32 s34, s0, s31
	s_cmp_ge_u32 s0, s31
	s_cselect_b32 s0, s34, s0
	s_sub_i32 s34, s0, s31
	s_cmp_ge_u32 s0, s31
	s_cselect_b32 s0, s34, s0
	s_xor_b32 s0, s0, s1
	s_sub_i32 s0, s0, s1
	s_add_i32 s1, s30, s8
	s_add_i32 s1, s1, s0
	v_lshl_add_u32 v4, s1, 8, v2
	v_ashrrev_i32_e32 v5, 31, v4
	v_lshl_add_u64 v[4:5], v[4:5], 2, s[20:21]
	global_load_dword v46, v[4:5], off
.LBB0_2017:
	s_or_b64 exec, exec, s[28:29]
	v_readlane_b32 s0, v253, 19
	v_mov_b64_e32 v[4:5], s[26:27]
	v_readlane_b32 s1, v253, 20
	s_nop 1
	v_cmp_ge_i64_e32 vcc, s[0:1], v[4:5]
	s_cbranch_vccnz .LBB0_2026
	s_and_saveexec_b64 s[28:29], s[14:15]
	s_cbranch_execz .LBB0_2020
	v_readlane_b32 s0, v253, 18
	s_or_b32 s0, s11, s0
	v_readlane_b32 s1, v253, 17
	s_mul_i32 s0, s0, s1
	v_readlane_b32 s1, v253, 16
	s_add_i32 s0, s0, s1
	s_ashr_i32 s1, s0, 31
	s_lshr_b32 s1, s1, 26
	s_add_i32 s1, s0, s1
	s_ashr_i32 s30, s1, 6
	s_lshl_b32 s30, s30, 3
	s_sub_i32 s31, s11, s30
	s_min_i32 s31, s31, 8
	s_abs_i32 s31, s31
	v_cvt_f32_u32_e32 v4, s31
	s_sub_i32 s34, 0, s31
	s_andn2_b32 s1, s1, 63
	s_sub_i32 s0, s0, s1
	v_rcp_iflag_f32_e32 v4, v4
	s_ashr_i32 s1, s0, 31
	s_abs_i32 s0, s0
	v_mul_f32_e32 v4, 0x4f7ffffe, v4
	v_cvt_u32_f32_e32 v4, v4
	s_nop 0
	v_readfirstlane_b32 s35, v4
	s_mul_i32 s34, s34, s35
	s_mul_hi_u32 s34, s35, s34
	s_add_i32 s35, s35, s34
	s_mul_hi_u32 s34, s0, s35
	s_mul_i32 s34, s34, s31
	s_sub_i32 s0, s0, s34
	s_sub_i32 s34, s0, s31
	s_cmp_ge_u32 s0, s31
	s_cselect_b32 s0, s34, s0
	s_sub_i32 s34, s0, s31
	s_cmp_ge_u32 s0, s31
	s_cselect_b32 s0, s34, s0
	s_xor_b32 s0, s0, s1
	s_sub_i32 s0, s0, s1
	s_add_i32 s1, s30, s8
	s_add_i32 s1, s1, s0
	v_lshl_add_u32 v4, s1, 8, v2
	v_ashrrev_i32_e32 v5, 31, v4
	v_lshl_add_u64 v[4:5], v[4:5], 2, s[20:21]
	global_load_dword v47, v[4:5], off
.LBB0_2020:
	s_or_b64 exec, exec, s[28:29]
	v_readlane_b32 s0, v253, 24
	v_mov_b64_e32 v[4:5], s[26:27]
	v_readlane_b32 s1, v253, 25
	s_nop 1
	v_cmp_ge_i64_e32 vcc, s[0:1], v[4:5]
	s_cbranch_vccnz .LBB0_2026
	s_and_saveexec_b64 s[28:29], s[14:15]
	s_cbranch_execz .LBB0_2023
	v_readlane_b32 s0, v253, 23
	s_or_b32 s0, s11, s0
	v_readlane_b32 s1, v253, 22
	s_mul_i32 s0, s0, s1
	v_readlane_b32 s1, v253, 21
	s_add_i32 s0, s0, s1
	s_ashr_i32 s1, s0, 31
	s_lshr_b32 s1, s1, 26
	s_add_i32 s1, s0, s1
	s_ashr_i32 s14, s1, 6
	s_lshl_b32 s14, s14, 3
	s_sub_i32 s15, s11, s14
	s_min_i32 s15, s15, 8
	s_abs_i32 s15, s15
	v_cvt_f32_u32_e32 v4, s15
	s_sub_i32 s30, 0, s15
	s_andn2_b32 s1, s1, 63
	s_sub_i32 s0, s0, s1
	v_rcp_iflag_f32_e32 v4, v4
	s_ashr_i32 s1, s0, 31
	s_abs_i32 s0, s0
	v_mul_f32_e32 v4, 0x4f7ffffe, v4
	v_cvt_u32_f32_e32 v4, v4
	s_nop 0
	v_readfirstlane_b32 s31, v4
	s_mul_i32 s30, s30, s31
	s_mul_hi_u32 s30, s31, s30
	s_add_i32 s31, s31, s30
	s_mul_hi_u32 s30, s0, s31
	s_mul_i32 s30, s30, s15
	s_sub_i32 s0, s0, s30
	s_sub_i32 s30, s0, s15
	s_cmp_ge_u32 s0, s15
	s_cselect_b32 s0, s30, s0
	s_sub_i32 s30, s0, s15
	s_cmp_ge_u32 s0, s15
	s_cselect_b32 s0, s30, s0
	s_xor_b32 s0, s0, s1
	s_sub_i32 s0, s0, s1
	s_add_i32 s1, s14, s8
	s_add_i32 s1, s1, s0
	v_lshl_add_u32 v4, s1, 8, v2
	v_ashrrev_i32_e32 v5, 31, v4
	v_lshl_add_u64 v[4:5], v[4:5], 2, s[20:21]
	global_load_dword v48, v[4:5], off
.LBB0_2023:
	s_or_b64 exec, exec, s[28:29]
	v_readlane_b32 s0, v253, 27
	v_mov_b64_e32 v[4:5], s[26:27]
	v_readlane_b32 s1, v253, 28
	s_nop 1
	v_cmp_lt_i64_e32 vcc, s[0:1], v[4:5]
	s_xor_b64 s[0:1], s[12:13], -1
	s_and_b64 s[0:1], vcc, s[0:1]
	s_and_saveexec_b64 s[12:13], s[0:1]
	s_cbranch_execz .LBB0_2025
	v_readlane_b32 s0, v253, 30
	s_or_b32 s0, s11, s0
	v_readlane_b32 s1, v253, 29
	s_mul_i32 s0, s0, s1
	v_readlane_b32 s1, v253, 26
	s_add_i32 s0, s0, s1
	s_ashr_i32 s1, s0, 31
	s_lshr_b32 s1, s1, 26
	s_add_i32 s1, s0, s1
	s_ashr_i32 s14, s1, 6
	s_lshl_b32 s14, s14, 3
	s_sub_i32 s15, s11, s14
	s_min_i32 s15, s15, 8
	s_abs_i32 s15, s15
	v_cvt_f32_u32_e32 v4, s15
	s_sub_i32 s28, 0, s15
	s_andn2_b32 s1, s1, 63
	s_sub_i32 s0, s0, s1
	v_rcp_iflag_f32_e32 v4, v4
	s_ashr_i32 s1, s0, 31
	s_abs_i32 s0, s0
	v_mul_f32_e32 v4, 0x4f7ffffe, v4
	v_cvt_u32_f32_e32 v4, v4
	s_nop 0
	v_readfirstlane_b32 s29, v4
	s_mul_i32 s28, s28, s29
	s_mul_hi_u32 s28, s29, s28
	s_add_i32 s29, s29, s28
	s_mul_hi_u32 s28, s0, s29
	s_mul_i32 s28, s28, s15
	s_sub_i32 s0, s0, s28
	s_sub_i32 s28, s0, s15
	s_cmp_ge_u32 s0, s15
	s_cselect_b32 s0, s28, s0
	s_sub_i32 s28, s0, s15
	s_cmp_ge_u32 s0, s15
	s_cselect_b32 s0, s28, s0
	s_xor_b32 s0, s0, s1
	s_sub_i32 s0, s0, s1
	s_add_i32 s1, s14, s8
	s_add_i32 s1, s1, s0
	v_lshl_add_u32 v4, s1, 8, v2
	v_ashrrev_i32_e32 v5, 31, v4
	v_lshl_add_u64 v[4:5], v[4:5], 2, s[20:21]
	global_load_dword v49, v[4:5], off

.LBB0_2686:
	s_sub_i32 s0, 0x200, s38
	s_min_i32 s41, s0, s90
	s_lshl_b32 s22, s41, 3
	s_ashr_i32 s23, s22, 31
	v_mov_b32_e32 v2, v0
	s_cmp_lt_i32 s2, s22
	s_cselect_b64 s[12:13], -1, 0
	s_cmp_ge_i32 s2, s22
	v_readfirstlane_b32 s42, v2
	s_cbranch_scc1 .Lgidx_skip_3
	s_movk_i32 s0, 0xff
	v_cmp_lt_i32_e64 s[6:7], s0, v2
	s_movk_i32 s0, 0x100
	v_lshl_add_u32 v3, v2, 2, s95
	v_cmp_gt_i32_e64 s[10:11], s0, v2
	s_and_saveexec_b64 s[24:25], s[10:11]
	s_cbranch_execz .LBB0_2689
	s_or_b32 s0, s41, s80
	s_mul_i32 s0, s0, s76
	s_add_i32 s0, s0, s91
	s_ashr_i32 s1, s0, 31
	s_lshr_b32 s1, s1, 26
	s_add_i32 s1, s0, s1
	s_ashr_i32 s26, s1, 6
	s_lshl_b32 s26, s26, 3
	s_sub_i32 s27, s41, s26
	s_min_i32 s27, s27, 8
	s_abs_i32 s27, s27
	v_cvt_f32_u32_e32 v4, s27
	s_sub_i32 s28, 0, s27
	s_andn2_b32 s1, s1, 63
	s_sub_i32 s0, s0, s1
	v_rcp_iflag_f32_e32 v4, v4
	s_ashr_i32 s1, s0, 31
	s_abs_i32 s0, s0
	v_mul_f32_e32 v4, 0x4f7ffffe, v4
	v_cvt_u32_f32_e32 v4, v4
	s_nop 0
	v_readfirstlane_b32 s29, v4
	s_mul_i32 s28, s28, s29
	s_mul_hi_u32 s28, s29, s28
	s_add_i32 s29, s29, s28
	s_mul_hi_u32 s28, s0, s29
	s_mul_i32 s28, s28, s27
	s_sub_i32 s0, s0, s28
	s_sub_i32 s28, s0, s27
	s_cmp_ge_u32 s0, s27
	s_cselect_b32 s0, s28, s0
	s_sub_i32 s28, s0, s27
	s_cmp_ge_u32 s0, s27
	s_cselect_b32 s0, s28, s0
	s_xor_b32 s0, s0, s1
	s_sub_i32 s0, s0, s1
	s_add_i32 s1, s26, s38
	s_add_i32 s1, s1, s0
	v_lshl_add_u32 v4, s1, 8, v2
	v_ashrrev_i32_e32 v5, 31, v4
	v_lshl_add_u64 v[4:5], v[4:5], 2, s[16:17]
	global_load_dword v34, v[4:5], off

.LBB0_2731:
	s_or_b64 exec, exec, s[24:25]
	v_readlane_b32 s0, v253, 27
	v_mov_b64_e32 v[4:5], s[22:23]
	v_readlane_b32 s1, v253, 28
	s_nop 1
	v_cmp_lt_i64_e32 vcc, s[0:1], v[4:5]
	s_xor_b64 s[0:1], s[6:7], -1
	s_and_b64 s[0:1], vcc, s[0:1]
	s_and_saveexec_b64 s[6:7], s[0:1]
	s_cbranch_execz .LBB0_2733
	v_readlane_b32 s0, v253, 30
	s_or_b32 s0, s41, s0
	v_readlane_b32 s1, v253, 29
	s_mul_i32 s0, s0, s1
	v_readlane_b32 s1, v253, 26
	s_add_i32 s0, s0, s1
	s_ashr_i32 s1, s0, 31
	s_lshr_b32 s1, s1, 26
	s_add_i32 s1, s0, s1
	s_ashr_i32 s10, s1, 6
	s_lshl_b32 s10, s10, 3
	s_sub_i32 s11, s41, s10
	s_min_i32 s11, s11, 8
	s_abs_i32 s11, s11
	v_cvt_f32_u32_e32 v4, s11
	s_sub_i32 s24, 0, s11
	s_andn2_b32 s1, s1, 63
	s_sub_i32 s0, s0, s1
	v_rcp_iflag_f32_e32 v4, v4
	s_ashr_i32 s1, s0, 31
	s_abs_i32 s0, s0
	v_mul_f32_e32 v4, 0x4f7ffffe, v4
	v_cvt_u32_f32_e32 v4, v4
	s_nop 0
	v_readfirstlane_b32 s25, v4
	s_mul_i32 s24, s24, s25
	s_mul_hi_u32 s24, s25, s24
	s_add_i32 s25, s25, s24
	s_mul_hi_u32 s24, s0, s25
	s_mul_i32 s24, s24, s11
	s_sub_i32 s0, s0, s24
	s_sub_i32 s24, s0, s11
	s_cmp_ge_u32 s0, s11
	s_cselect_b32 s0, s24, s0
	s_sub_i32 s24, s0, s11
	s_cmp_ge_u32 s0, s11
	s_cselect_b32 s0, s24, s0
	s_xor_b32 s0, s0, s1
	s_sub_i32 s0, s0, s1
	s_add_i32 s1, s10, s38
	s_add_i32 s1, s1, s0
	v_lshl_add_u32 v4, s1, 8, v2
	v_ashrrev_i32_e32 v5, 31, v4
	v_lshl_add_u64 v[4:5], v[4:5], 2, s[16:17]
	global_load_dword v49, v[4:5], off

	.amdhsa_kernel _Z10fwd_kernelILi0ELi34EEv4Args
		.amdhsa_group_segment_fixed_size 0
		.amdhsa_private_segment_fixed_size 0
		.amdhsa_kernarg_size 528
		.amdhsa_user_sgpr_count 2
		.amdhsa_user_sgpr_dispatch_ptr 0
		.amdhsa_user_sgpr_queue_ptr 0
		.amdhsa_user_sgpr_kernarg_segment_ptr 1
		.amdhsa_user_sgpr_dispatch_id 0
		.amdhsa_user_sgpr_kernarg_preload_length 0
		.amdhsa_user_sgpr_kernarg_preload_offset 0
		.amdhsa_user_sgpr_private_segment_size 0
		.amdhsa_uses_dynamic_stack 0
		.amdhsa_enable_private_segment 0
		.amdhsa_system_sgpr_workgroup_id_x 1
		.amdhsa_system_sgpr_workgroup_id_y 0
		.amdhsa_system_sgpr_workgroup_id_z 0
		.amdhsa_system_sgpr_workgroup_info 0
		.amdhsa_system_vgpr_workitem_id 0
		.amdhsa_next_free_vgpr 255
		.amdhsa_next_free_sgpr 102
		.amdhsa_accum_offset 256
		.amdhsa_reserve_vcc 1
		.amdhsa_float_round_mode_32 0
		.amdhsa_float_round_mode_16_64 0
		.amdhsa_float_denorm_mode_32 3
		.amdhsa_float_denorm_mode_16_64 3
		.amdhsa_dx10_clamp 1
		.amdhsa_ieee_mode 1
		.amdhsa_fp16_overflow 0
		.amdhsa_tg_split 0
		.amdhsa_exception_fp_ieee_invalid_op 0
		.amdhsa_exception_fp_denorm_src 0
		.amdhsa_exception_fp_ieee_div_zero 0
		.amdhsa_exception_fp_ieee_overflow 0
		.amdhsa_exception_fp_ieee_underflow 0
		.amdhsa_exception_fp_ieee_inexact 0
		.amdhsa_exception_int_div_zero 0
	.end_amdhsa_kernel

amdhsa.kernels:
  - .agpr_count:     0
    .args:
      - .offset:         0
        .size:           272
        .value_kind:     by_value
      - .offset:         272
        .size:           4
        .value_kind:     hidden_block_count_x
      - .offset:         276
        .size:           4
        .value_kind:     hidden_block_count_y
      - .offset:         280
        .size:           4
        .value_kind:     hidden_block_count_z
      - .offset:         284
        .size:           2
        .value_kind:     hidden_group_size_x
      - .offset:         286
        .size:           2
        .value_kind:     hidden_group_size_y
      - .offset:         288
        .size:           2
        .value_kind:     hidden_group_size_z
      - .offset:         290
        .size:           2
        .value_kind:     hidden_remainder_x
      - .offset:         292
        .size:           2
        .value_kind:     hidden_remainder_y
      - .offset:         294
        .size:           2
        .value_kind:     hidden_remainder_z
      - .offset:         312
        .size:           8
        .value_kind:     hidden_global_offset_x
      - .offset:         320
        .size:           8
        .value_kind:     hidden_global_offset_y
      - .offset:         328
        .size:           8
        .value_kind:     hidden_global_offset_z
      - .offset:         336
        .size:           2
        .value_kind:     hidden_grid_dims
      - .offset:         392
        .size:           4
        .value_kind:     hidden_dynamic_lds_size
    .group_segment_fixed_size: 0
    .kernarg_segment_align: 8
    .kernarg_segment_size: 528
    .language:       OpenCL C
    .language_version:
      - 2
      - 0
    .max_flat_workgroup_size: 512
    .name:           _Z10fwd_kernelILi0ELi34EEv4Args
    .private_segment_fixed_size: 0
    .sgpr_count:     108
    .sgpr_spill_count: 117
    .symbol:         _Z10fwd_kernelILi0ELi34EEv4Args.kd
    .uniform_work_group_size: 1
    .uses_dynamic_stack: false
    .vgpr_count:     255
    .vgpr_spill_count: 0
    .wavefront_size: 64
